# P5/P8 EpiRes epilogues: xor-16/xor-32 ssq reductions via v_permlane16/32_swap instead of ds_bpermute round trips
# baseline (speedup 1.0000x reference)
.LBB0_883:
	ds_read_b128 v[128:131], v186
	ds_read_b128 v[132:135], v186 offset:1024
	ds_read_b128 v[136:139], v186 offset:2048
	ds_read_b128 v[140:143], v186 offset:3072
	s_add_u32 s28, s26, 0xfffc0080
	s_addc_u32 s29, s27, -1
	s_cmp_eq_u32 s40, 12
	s_cselect_b32 s31, s25, s29
	s_cselect_b32 s30, s34, s28
	s_cselect_b32 s29, s36, s39
	s_cselect_b32 s28, s37, s38
	v_lshl_add_u64 v[182:183], s[26:27], 0, v[164:165]
	s_add_i32 m0, s45, 0xc000
	ds_read_b128 v[144:147], v187
	ds_read_b128 v[148:151], v187 offset:1024
	ds_read_b128 v[152:155], v187 offset:2048
	ds_read_b128 v[156:159], v187 offset:3072
	ds_read_b128 v[170:173], v187 offset:4096
	ds_read_b128 v[174:177], v187 offset:5120
	ds_read_b128 v[178:181], v187 offset:6144
	ds_read_b128 v[192:195], v187 offset:7168
	global_load_lds_dwordx4 v[182:183], off
	v_lshl_add_u64 v[182:183], s[26:27], 0, v[166:167]
	s_add_i32 m0, s45, 0xe000
	s_nop 0
	global_load_lds_dwordx4 v[182:183], off
	ds_read_b128 v[196:199], v188
	ds_read_b128 v[204:207], v188 offset:1024
	ds_read_b128 v[208:211], v188 offset:2048
	ds_read_b128 v[212:215], v188 offset:3072
	s_waitcnt lgkmcnt(0)
	s_waitcnt vmcnt(8)
	s_barrier
	s_setprio 1
	v_mfma_f32_16x16x32_bf16 v[124:127], v[128:131], v[144:147], v[124:127]
	v_mfma_f32_16x16x32_bf16 v[120:123], v[136:139], v[144:147], v[120:123]
	v_mfma_f32_16x16x32_bf16 v[108:111], v[128:131], v[152:155], v[108:111]
	v_mfma_f32_16x16x32_bf16 v[104:107], v[136:139], v[152:155], v[104:107]
	v_mfma_f32_16x16x32_bf16 v[92:95], v[128:131], v[170:173], v[92:95]
	v_mfma_f32_16x16x32_bf16 v[88:91], v[136:139], v[170:173], v[88:91]
	v_mfma_f32_16x16x32_bf16 v[76:79], v[128:131], v[178:181], v[76:79]
	v_mfma_f32_16x16x32_bf16 v[72:75], v[136:139], v[178:181], v[72:75]
	v_mfma_f32_16x16x32_bf16 v[124:127], v[132:135], v[148:151], v[124:127]
	v_mfma_f32_16x16x32_bf16 v[120:123], v[140:143], v[148:151], v[120:123]
	v_mfma_f32_16x16x32_bf16 v[108:111], v[132:135], v[156:159], v[108:111]
	v_mfma_f32_16x16x32_bf16 v[104:107], v[140:143], v[156:159], v[104:107]
	v_mfma_f32_16x16x32_bf16 v[92:95], v[132:135], v[174:177], v[92:95]
	v_mfma_f32_16x16x32_bf16 v[88:91], v[140:143], v[174:177], v[88:91]
	v_mfma_f32_16x16x32_bf16 v[76:79], v[132:135], v[192:195], v[76:79]
	v_mfma_f32_16x16x32_bf16 v[72:75], v[140:143], v[192:195], v[72:75]
	v_mfma_f32_16x16x32_bf16 v[116:119], v[196:199], v[144:147], v[116:119]
	v_mfma_f32_16x16x32_bf16 v[112:115], v[208:211], v[144:147], v[112:115]
	v_mfma_f32_16x16x32_bf16 v[100:103], v[196:199], v[152:155], v[100:103]
	v_mfma_f32_16x16x32_bf16 v[96:99], v[208:211], v[152:155], v[96:99]
	v_mfma_f32_16x16x32_bf16 v[84:87], v[196:199], v[170:173], v[84:87]
	v_mfma_f32_16x16x32_bf16 v[80:83], v[208:211], v[170:173], v[80:83]
	v_mfma_f32_16x16x32_bf16 v[68:71], v[196:199], v[178:181], v[68:71]
	v_mfma_f32_16x16x32_bf16 v[64:67], v[208:211], v[178:181], v[64:67]
	v_mfma_f32_16x16x32_bf16 v[116:119], v[204:207], v[148:151], v[116:119]
	v_mfma_f32_16x16x32_bf16 v[112:115], v[212:215], v[148:151], v[112:115]
	v_mfma_f32_16x16x32_bf16 v[100:103], v[204:207], v[156:159], v[100:103]
	v_mfma_f32_16x16x32_bf16 v[96:99], v[212:215], v[156:159], v[96:99]
	v_mfma_f32_16x16x32_bf16 v[84:87], v[204:207], v[174:177], v[84:87]
	v_mfma_f32_16x16x32_bf16 v[80:83], v[212:215], v[174:177], v[80:83]
	v_mfma_f32_16x16x32_bf16 v[68:71], v[204:207], v[192:195], v[68:71]
	v_mfma_f32_16x16x32_bf16 v[64:67], v[212:215], v[192:195], v[64:67]
	s_setprio 0
	s_barrier
	ds_read_b128 v[144:147], v187 offset:16384
	ds_read_b128 v[148:151], v187 offset:17408
	ds_read_b128 v[152:155], v187 offset:18432
	ds_read_b128 v[156:159], v187 offset:19456
	ds_read_b128 v[170:173], v187 offset:20480
	ds_read_b128 v[174:177], v187 offset:21504
	ds_read_b128 v[178:181], v187 offset:22528
	ds_read_b128 v[192:195], v187 offset:23552
	s_mov_b32 m0, s43
	v_lshl_add_u64 v[182:183], s[28:29], 0, v[160:161]
	global_load_lds_dwordx4 v[182:183], off
	v_lshl_add_u64 v[200:201], s[28:29], 0, v[162:163]
	s_mov_b32 m0, s44
	s_nop 0
	global_load_lds_dwordx4 v[200:201], off
	s_mov_b32 m0, s45
	v_lshl_add_u64 v[216:217], s[30:31], 0, v[160:161]
	global_load_lds_dwordx4 v[216:217], off
	v_lshl_add_u64 v[218:219], s[30:31], 0, v[162:163]
	s_mov_b32 m0, s46
	s_nop 0
	global_load_lds_dwordx4 v[218:219], off
	s_add_u32 s66, s28, 0x40000
	s_addc_u32 s67, s29, 0
	s_mov_b32 m0, s47
	v_lshl_add_u64 v[248:249], s[66:67], 0, v[160:161]
	global_load_lds_dwordx4 v[248:249], off
	v_lshl_add_u64 v[248:249], s[66:67], 0, v[162:163]
	s_mov_b32 m0, s48
	s_nop 0
	global_load_lds_dwordx4 v[248:249], off
	s_waitcnt lgkmcnt(0)
	s_waitcnt vmcnt(8)
	s_barrier
	s_setprio 1
	v_mfma_f32_16x16x32_bf16 v[60:63], v[128:131], v[144:147], v[60:63]
	v_mfma_f32_16x16x32_bf16 v[56:59], v[136:139], v[144:147], v[56:59]
	v_mfma_f32_16x16x32_bf16 v[44:47], v[128:131], v[152:155], v[44:47]
	v_mfma_f32_16x16x32_bf16 v[40:43], v[136:139], v[152:155], v[40:43]
	v_mfma_f32_16x16x32_bf16 v[28:31], v[128:131], v[170:173], v[28:31]
	v_mfma_f32_16x16x32_bf16 v[24:27], v[136:139], v[170:173], v[24:27]
	v_mfma_f32_16x16x32_bf16 v[12:15], v[128:131], v[178:181], v[12:15]
	v_mfma_f32_16x16x32_bf16 v[8:11], v[136:139], v[178:181], v[8:11]
	v_mfma_f32_16x16x32_bf16 v[60:63], v[132:135], v[148:151], v[60:63]
	v_mfma_f32_16x16x32_bf16 v[56:59], v[140:143], v[148:151], v[56:59]
	v_mfma_f32_16x16x32_bf16 v[44:47], v[132:135], v[156:159], v[44:47]
	v_mfma_f32_16x16x32_bf16 v[40:43], v[140:143], v[156:159], v[40:43]
	v_mfma_f32_16x16x32_bf16 v[28:31], v[132:135], v[174:177], v[28:31]
	v_mfma_f32_16x16x32_bf16 v[24:27], v[140:143], v[174:177], v[24:27]
	v_mfma_f32_16x16x32_bf16 v[12:15], v[132:135], v[192:195], v[12:15]
	v_mfma_f32_16x16x32_bf16 v[8:11], v[140:143], v[192:195], v[8:11]
	v_mfma_f32_16x16x32_bf16 v[52:55], v[196:199], v[144:147], v[52:55]
	v_mfma_f32_16x16x32_bf16 v[48:51], v[208:211], v[144:147], v[48:51]
	v_mfma_f32_16x16x32_bf16 v[36:39], v[196:199], v[152:155], v[36:39]
	v_mfma_f32_16x16x32_bf16 v[32:35], v[208:211], v[152:155], v[32:35]
	v_mfma_f32_16x16x32_bf16 v[20:23], v[196:199], v[170:173], v[20:23]
	v_mfma_f32_16x16x32_bf16 v[16:19], v[208:211], v[170:173], v[16:19]
	v_mfma_f32_16x16x32_bf16 v[4:7], v[196:199], v[178:181], v[4:7]
	v_mfma_f32_16x16x32_bf16 v[0:3], v[208:211], v[178:181], v[0:3]
	v_mfma_f32_16x16x32_bf16 v[52:55], v[204:207], v[148:151], v[52:55]
	v_mfma_f32_16x16x32_bf16 v[48:51], v[212:215], v[148:151], v[48:51]
	v_mfma_f32_16x16x32_bf16 v[36:39], v[204:207], v[156:159], v[36:39]
	v_mfma_f32_16x16x32_bf16 v[32:35], v[212:215], v[156:159], v[32:35]
	v_mfma_f32_16x16x32_bf16 v[20:23], v[204:207], v[174:177], v[20:23]
	v_mfma_f32_16x16x32_bf16 v[16:19], v[212:215], v[174:177], v[16:19]
	v_mfma_f32_16x16x32_bf16 v[4:7], v[204:207], v[192:195], v[4:7]
	v_mfma_f32_16x16x32_bf16 v[0:3], v[212:215], v[192:195], v[0:3]
	s_setprio 0
	s_barrier
	ds_read_b128 v[128:131], v189
	ds_read_b128 v[132:135], v189 offset:1024
	ds_read_b128 v[136:139], v189 offset:2048
	ds_read_b128 v[140:143], v189 offset:3072
	s_add_u32 s30, s30, 0x40000
	s_addc_u32 s31, s31, 0
	s_mov_b32 m0, s49
	v_lshl_add_u64 v[196:197], s[30:31], 0, v[160:161]
	ds_read_b128 v[144:147], v187 offset:32768
	ds_read_b128 v[148:151], v187 offset:33792
	ds_read_b128 v[152:155], v187 offset:34816
	ds_read_b128 v[156:159], v187 offset:35840
	ds_read_b128 v[170:173], v187 offset:36864
	ds_read_b128 v[174:177], v187 offset:37888
	ds_read_b128 v[178:181], v187 offset:38912
	ds_read_b128 v[192:195], v187 offset:39936
	global_load_lds_dwordx4 v[196:197], off
	v_lshl_add_u64 v[196:197], s[30:31], 0, v[162:163]
	s_mov_b32 m0, s50
	s_nop 0
	global_load_lds_dwordx4 v[196:197], off
	ds_read_b128 v[196:199], v190
	ds_read_b128 v[204:207], v190 offset:1024
	ds_read_b128 v[208:211], v190 offset:2048
	ds_read_b128 v[212:215], v190 offset:3072
	s_waitcnt lgkmcnt(0)
	s_waitcnt vmcnt(8)
	s_barrier
	s_setprio 1
	v_mfma_f32_16x16x32_bf16 v[124:127], v[128:131], v[144:147], v[124:127]
	v_mfma_f32_16x16x32_bf16 v[120:123], v[136:139], v[144:147], v[120:123]
	v_mfma_f32_16x16x32_bf16 v[108:111], v[128:131], v[152:155], v[108:111]
	v_mfma_f32_16x16x32_bf16 v[104:107], v[136:139], v[152:155], v[104:107]
	v_mfma_f32_16x16x32_bf16 v[92:95], v[128:131], v[170:173], v[92:95]
	v_mfma_f32_16x16x32_bf16 v[88:91], v[136:139], v[170:173], v[88:91]
	v_mfma_f32_16x16x32_bf16 v[76:79], v[128:131], v[178:181], v[76:79]
	v_mfma_f32_16x16x32_bf16 v[72:75], v[136:139], v[178:181], v[72:75]
	v_mfma_f32_16x16x32_bf16 v[124:127], v[132:135], v[148:151], v[124:127]
	v_mfma_f32_16x16x32_bf16 v[120:123], v[140:143], v[148:151], v[120:123]
	v_mfma_f32_16x16x32_bf16 v[108:111], v[132:135], v[156:159], v[108:111]
	v_mfma_f32_16x16x32_bf16 v[104:107], v[140:143], v[156:159], v[104:107]
	v_mfma_f32_16x16x32_bf16 v[92:95], v[132:135], v[174:177], v[92:95]
	v_mfma_f32_16x16x32_bf16 v[88:91], v[140:143], v[174:177], v[88:91]
	v_mfma_f32_16x16x32_bf16 v[76:79], v[132:135], v[192:195], v[76:79]
	v_mfma_f32_16x16x32_bf16 v[72:75], v[140:143], v[192:195], v[72:75]
	v_mfma_f32_16x16x32_bf16 v[116:119], v[196:199], v[144:147], v[116:119]
	v_mfma_f32_16x16x32_bf16 v[112:115], v[208:211], v[144:147], v[112:115]
	v_mfma_f32_16x16x32_bf16 v[100:103], v[196:199], v[152:155], v[100:103]
	v_mfma_f32_16x16x32_bf16 v[96:99], v[208:211], v[152:155], v[96:99]
	v_mfma_f32_16x16x32_bf16 v[84:87], v[196:199], v[170:173], v[84:87]
	v_mfma_f32_16x16x32_bf16 v[80:83], v[208:211], v[170:173], v[80:83]
	v_mfma_f32_16x16x32_bf16 v[68:71], v[196:199], v[178:181], v[68:71]
	v_mfma_f32_16x16x32_bf16 v[64:67], v[208:211], v[178:181], v[64:67]
	v_mfma_f32_16x16x32_bf16 v[116:119], v[204:207], v[148:151], v[116:119]
	v_mfma_f32_16x16x32_bf16 v[112:115], v[212:215], v[148:151], v[112:115]
	v_mfma_f32_16x16x32_bf16 v[100:103], v[204:207], v[156:159], v[100:103]
	v_mfma_f32_16x16x32_bf16 v[96:99], v[212:215], v[156:159], v[96:99]
	v_mfma_f32_16x16x32_bf16 v[84:87], v[204:207], v[174:177], v[84:87]
	v_mfma_f32_16x16x32_bf16 v[80:83], v[212:215], v[174:177], v[80:83]
	v_mfma_f32_16x16x32_bf16 v[68:71], v[204:207], v[192:195], v[68:71]
	v_mfma_f32_16x16x32_bf16 v[64:67], v[212:215], v[192:195], v[64:67]
	s_setprio 0
	s_barrier
	ds_read_b128 v[144:147], v187 offset:49152
	ds_read_b128 v[148:151], v187 offset:50176
	ds_read_b128 v[152:155], v187 offset:51200
	ds_read_b128 v[156:159], v187 offset:52224
	ds_read_b128 v[170:173], v187 offset:53248
	ds_read_b128 v[174:177], v187 offset:54272
	ds_read_b128 v[178:181], v187 offset:55296
	ds_read_b128 v[192:195], v187 offset:56320
	s_mov_b32 m0, s54
	v_lshl_add_u64 v[182:183], v[182:183], 0, s[12:13]
	global_load_lds_dwordx4 v[182:183], off
	v_lshl_add_u64 v[182:183], v[200:201], 0, s[12:13]
	s_mov_b32 m0, s55
	s_nop 0
	global_load_lds_dwordx4 v[182:183], off
	s_mov_b32 m0, s56
	v_lshl_add_u64 v[182:183], v[216:217], 0, s[12:13]
	global_load_lds_dwordx4 v[182:183], off
	v_lshl_add_u64 v[182:183], v[218:219], 0, s[12:13]
	s_mov_b32 m0, s57
	s_nop 0
	global_load_lds_dwordx4 v[182:183], off
	s_add_u32 s28, s28, 0x40080
	s_addc_u32 s29, s29, 0
	s_mov_b32 m0, s58
	v_lshl_add_u64 v[248:249], s[28:29], 0, v[160:161]
	global_load_lds_dwordx4 v[248:249], off
	v_lshl_add_u64 v[248:249], s[28:29], 0, v[162:163]
	s_mov_b32 m0, s59
	s_nop 0
	global_load_lds_dwordx4 v[248:249], off
	s_waitcnt lgkmcnt(0)
	s_waitcnt vmcnt(8)
	s_barrier
	s_setprio 1
	v_mfma_f32_16x16x32_bf16 v[60:63], v[128:131], v[144:147], v[60:63]
	v_mfma_f32_16x16x32_bf16 v[56:59], v[136:139], v[144:147], v[56:59]
	v_mfma_f32_16x16x32_bf16 v[44:47], v[128:131], v[152:155], v[44:47]
	v_mfma_f32_16x16x32_bf16 v[40:43], v[136:139], v[152:155], v[40:43]
	v_mfma_f32_16x16x32_bf16 v[28:31], v[128:131], v[170:173], v[28:31]
	v_mfma_f32_16x16x32_bf16 v[24:27], v[136:139], v[170:173], v[24:27]
	v_mfma_f32_16x16x32_bf16 v[12:15], v[128:131], v[178:181], v[12:15]
	v_mfma_f32_16x16x32_bf16 v[8:11], v[136:139], v[178:181], v[8:11]
	v_mfma_f32_16x16x32_bf16 v[60:63], v[132:135], v[148:151], v[60:63]
	v_mfma_f32_16x16x32_bf16 v[56:59], v[140:143], v[148:151], v[56:59]
	v_mfma_f32_16x16x32_bf16 v[44:47], v[132:135], v[156:159], v[44:47]
	v_mfma_f32_16x16x32_bf16 v[40:43], v[140:143], v[156:159], v[40:43]
	v_mfma_f32_16x16x32_bf16 v[28:31], v[132:135], v[174:177], v[28:31]
	v_mfma_f32_16x16x32_bf16 v[24:27], v[140:143], v[174:177], v[24:27]
	v_mfma_f32_16x16x32_bf16 v[12:15], v[132:135], v[192:195], v[12:15]
	v_mfma_f32_16x16x32_bf16 v[8:11], v[140:143], v[192:195], v[8:11]
	v_mfma_f32_16x16x32_bf16 v[52:55], v[196:199], v[144:147], v[52:55]
	v_mfma_f32_16x16x32_bf16 v[48:51], v[208:211], v[144:147], v[48:51]
	v_mfma_f32_16x16x32_bf16 v[36:39], v[196:199], v[152:155], v[36:39]
	v_mfma_f32_16x16x32_bf16 v[32:35], v[208:211], v[152:155], v[32:35]
	v_mfma_f32_16x16x32_bf16 v[20:23], v[196:199], v[170:173], v[20:23]
	v_mfma_f32_16x16x32_bf16 v[16:19], v[208:211], v[170:173], v[16:19]
	v_mfma_f32_16x16x32_bf16 v[4:7], v[196:199], v[178:181], v[4:7]
	v_mfma_f32_16x16x32_bf16 v[0:3], v[208:211], v[178:181], v[0:3]
	v_mfma_f32_16x16x32_bf16 v[52:55], v[204:207], v[148:151], v[52:55]
	v_mfma_f32_16x16x32_bf16 v[48:51], v[212:215], v[148:151], v[48:51]
	v_mfma_f32_16x16x32_bf16 v[36:39], v[204:207], v[156:159], v[36:39]
	v_mfma_f32_16x16x32_bf16 v[32:35], v[212:215], v[156:159], v[32:35]
	v_mfma_f32_16x16x32_bf16 v[20:23], v[204:207], v[174:177], v[20:23]
	v_mfma_f32_16x16x32_bf16 v[16:19], v[212:215], v[174:177], v[16:19]
	v_mfma_f32_16x16x32_bf16 v[4:7], v[204:207], v[192:195], v[4:7]
	v_mfma_f32_16x16x32_bf16 v[0:3], v[212:215], v[192:195], v[0:3]
	s_setprio 0
	s_add_i32 s40, s40, 2
	s_add_u32 s26, s26, 0x100
	s_addc_u32 s27, s27, 0
	s_add_u32 s38, s38, 0x100
	s_addc_u32 s39, s39, 0
	s_cmp_gt_u32 s40, 13
	s_barrier
	s_cbranch_scc0 .LBB0_883
	v_lshl_or_b32 v128, s65, 8, v185
	v_lshl_add_u32 v170, s24, 8, v184
	v_ashrrev_i32_e32 v129, 31, v128
	v_lshlrev_b64 v[174:175], 1, v[128:129]
	v_ashrrev_i32_e32 v171, 31, v170
	v_lshl_add_u64 v[128:129], s[10:11], 0, v[174:175]
	v_lshlrev_b64 v[204:205], 11, v[170:171]
	v_lshl_add_u64 v[130:131], v[128:129], 0, v[204:205]
	v_mov_b32_e32 v194, v220
	v_mov_b32_e32 v195, v221
	v_mov_b32_e32 v196, v222
	v_mov_b32_e32 v197, v223
	v_mov_b32_e32 v198, v224
	v_mov_b32_e32 v199, v225
	v_mov_b32_e32 v200, v226
	v_mov_b32_e32 v201, v227
	v_or_b32_e32 v130, 16, v170
	v_or_b32_e32 v132, 32, v170
	v_or_b32_e32 v134, 48, v170
	v_ashrrev_i32_e32 v131, 31, v130
	v_ashrrev_i32_e32 v133, 31, v132
	v_ashrrev_i32_e32 v135, 31, v134
	v_lshlrev_b64 v[182:183], 11, v[130:131]
	v_add_u32_e32 v178, 0x80, v170
	v_lshlrev_b64 v[180:181], 11, v[132:133]
	v_lshlrev_b64 v[176:177], 11, v[134:135]
	v_lshl_add_u64 v[132:133], v[128:129], 0, v[182:183]
	v_ashrrev_i32_e32 v179, 31, v178
	v_lshl_add_u64 v[134:135], v[128:129], 0, v[180:181]
	v_lshl_add_u64 v[128:129], v[128:129], 0, v[176:177]
	v_mov_b32_e32 v156, v228
	v_mov_b32_e32 v157, v229
	v_mov_b32_e32 v158, v230
	v_mov_b32_e32 v159, v231
	v_mov_b32_e32 v152, v232
	v_mov_b32_e32 v153, v233
	v_mov_b32_e32 v154, v234
	v_mov_b32_e32 v155, v235
	v_mov_b32_e32 v148, v236
	v_mov_b32_e32 v149, v237
	v_mov_b32_e32 v150, v238
	v_mov_b32_e32 v151, v239
	v_mov_b32_e32 v144, v240
	v_mov_b32_e32 v145, v241
	v_mov_b32_e32 v146, v242
	v_mov_b32_e32 v147, v243
	v_mov_b32_e32 v140, v252
	v_mov_b32_e32 v141, v253
	v_mov_b32_e32 v142, v254
	v_mov_b32_e32 v143, v255
	global_load_dwordx4 v[136:139], v[128:129], off offset:64
	v_lshlrev_b64 v[130:131], 11, v[178:179]
	v_lshl_add_u64 v[130:131], s[10:11], 0, v[130:131]
	v_lshl_add_u64 v[172:173], v[130:131], 0, v[174:175]
	global_load_dwordx4 v[132:135], v[172:173], off
	global_load_dwordx4 v[128:131], v[172:173], off offset:64
	v_and_b32_e32 v192, 64, v191
	v_xor_b32_e32 v179, 16, v191
	v_add_u32_e32 v192, 64, v192
	v_xor_b32_e32 v193, 32, v191
	v_cmp_lt_i32_e32 vcc, v179, v192
	v_lshl_add_u64 v[204:205], s[10:11], 0, v[204:205]
	v_lshl_add_u64 v[204:205], v[204:205], 0, v[174:175]
	v_cndmask_b32_e32 v179, v191, v179, vcc
	v_cmp_lt_i32_e32 vcc, v193, v192
	v_lshlrev_b32_e32 v192, 2, v179
	s_lshl_b32 s24, s65, 2
	v_cndmask_b32_e32 v193, v191, v193, vcc
	v_lshlrev_b32_e32 v179, 2, v193
	s_or_b32 s27, s24, s53
	s_mul_hi_i32 s26, s27, 0x21000
	s_mul_i32 s27, s27, 0x21000
	v_lshlrev_b32_e32 v206, 16, v194
	v_and_b32_e32 v207, 0xffff0000, v194
	v_lshlrev_b32_e32 v194, 16, v195
	v_and_b32_e32 v195, 0xffff0000, v195
	v_lshlrev_b32_e32 v208, 16, v196
	v_and_b32_e32 v209, 0xffff0000, v196
	v_lshlrev_b32_e32 v196, 16, v197
	v_and_b32_e32 v197, 0xffff0000, v197
	v_lshlrev_b32_e32 v212, 16, v200
	v_and_b32_e32 v213, 0xffff0000, v200
	v_lshlrev_b32_e32 v200, 16, v201
	v_and_b32_e32 v201, 0xffff0000, v201
	v_pk_add_f32 v[126:127], v[126:127], v[194:195]
	v_pk_add_f32 v[124:125], v[124:125], v[206:207]
	v_pk_add_f32 v[122:123], v[122:123], v[196:197]
	v_pk_add_f32 v[120:121], v[120:121], v[208:209]
	v_lshlrev_b32_e32 v210, 16, v198
	v_and_b32_e32 v211, 0xffff0000, v198
	v_lshlrev_b32_e32 v198, 16, v199
	v_and_b32_e32 v199, 0xffff0000, v199
	v_pk_add_f32 v[194:195], v[114:115], v[200:201]
	v_pk_add_f32 v[196:197], v[112:113], v[212:213]
	v_cvt_pk_bf16_f32 v112, v124, v125
	v_cvt_pk_bf16_f32 v113, v126, v127
	v_mul_f32_e32 v114, v125, v125
	v_mul_f32_e32 v115, v127, v127
	v_mul_f32_e32 v125, v121, v121
	v_mul_f32_e32 v127, v123, v123
	v_pk_add_f32 v[118:119], v[118:119], v[198:199]
	v_pk_add_f32 v[116:117], v[116:117], v[210:211]
	v_fmac_f32_e32 v114, v124, v124
	v_fmac_f32_e32 v115, v126, v126
	v_fmac_f32_e32 v125, v120, v120
	v_fmac_f32_e32 v127, v122, v122
	v_mul_f32_e32 v193, v117, v117
	v_mul_f32_e32 v198, v119, v119
	v_add_f32_e32 v114, v114, v115
	v_add_f32_e32 v115, v125, v127
	v_mul_f32_e32 v124, v197, v197
	v_mul_f32_e32 v125, v195, v195
	v_fmac_f32_e32 v193, v116, v116
	v_fmac_f32_e32 v198, v118, v118
	v_fmac_f32_e32 v124, v196, v196
	v_fmac_f32_e32 v125, v194, v194
	v_add_f32_e32 v114, v114, v115
	v_add_f32_e32 v115, v193, v198
	v_add_f32_e32 v124, v124, v125
	v_add_f32_e32 v115, v115, v124
	v_add_f32_e32 v124, v114, v115
	v_mov_b32_e32 v125, v124
	s_nop 1
	v_permlane16_swap_b32_e32 v124, v125
	v_cvt_pk_bf16_f32 v114, v120, v121
	v_cvt_pk_bf16_f32 v115, v122, v123
	global_store_dwordx4 v[204:205], v[112:115], off
	s_waitcnt lgkmcnt(0)
	s_nop 0
	v_add_f32_e32 v112, v124, v125
	v_mov_b32_e32 v113, v112
	s_nop 1
	v_permlane32_swap_b32_e32 v112, v113
	v_cvt_pk_bf16_f32 v114, v116, v117
	v_cvt_pk_bf16_f32 v115, v118, v119
	v_cvt_pk_bf16_f32 v116, v196, v197
	v_cvt_pk_bf16_f32 v117, v194, v195
	global_store_dwordx4 v[204:205], v[114:117], off offset:64
	s_and_saveexec_b64 s[24:25], s[4:5]
	s_cbranch_execz .LBB0_886
	s_add_u32 s28, s51, s27
	s_addc_u32 s29, s52, s26
	s_waitcnt lgkmcnt(0)
	v_add_f32_e32 v114, v112, v113
	v_lshl_add_u64 v[112:113], v[170:171], 2, s[28:29]
	global_store_dword v[112:113], v114, off
.LBB0_886:
	s_or_b64 exec, exec, s[24:25]
	v_or_b32_e32 v112, 16, v178
	s_waitcnt lgkmcnt(0)
	v_ashrrev_i32_e32 v113, 31, v112
	v_lshlrev_b64 v[112:113], 11, v[112:113]
	v_lshl_add_u64 v[112:113], s[10:11], 0, v[112:113]
	v_lshl_add_u64 v[120:121], v[112:113], 0, v[174:175]
	global_load_dwordx4 v[116:119], v[120:121], off
	global_load_dwordx4 v[112:115], v[120:121], off offset:64
	v_lshlrev_b32_e32 v124, 16, v157
	v_and_b32_e32 v125, 0xffff0000, v157
	v_lshlrev_b32_e32 v122, 16, v156
	v_and_b32_e32 v123, 0xffff0000, v156
	v_pk_add_f32 v[110:111], v[110:111], v[124:125]
	v_lshlrev_b32_e32 v124, 16, v159
	v_and_b32_e32 v125, 0xffff0000, v159
	v_pk_add_f32 v[108:109], v[108:109], v[122:123]
	v_lshlrev_b32_e32 v122, 16, v158
	v_and_b32_e32 v123, 0xffff0000, v158
	v_pk_add_f32 v[106:107], v[106:107], v[124:125]
	v_lshlrev_b32_e32 v124, 16, v153
	v_and_b32_e32 v125, 0xffff0000, v153
	v_pk_add_f32 v[104:105], v[104:105], v[122:123]
	v_lshlrev_b32_e32 v122, 16, v152
	v_and_b32_e32 v123, 0xffff0000, v152
	v_pk_add_f32 v[102:103], v[102:103], v[124:125]
	v_lshlrev_b32_e32 v124, 16, v155
	v_and_b32_e32 v125, 0xffff0000, v155
	v_pk_add_f32 v[100:101], v[100:101], v[122:123]
	v_lshlrev_b32_e32 v122, 16, v154
	v_and_b32_e32 v123, 0xffff0000, v154
	v_pk_add_f32 v[124:125], v[98:99], v[124:125]
	v_mul_f32_e32 v98, v109, v109
	v_mul_f32_e32 v99, v111, v111
	v_pk_add_f32 v[122:123], v[96:97], v[122:123]
	v_lshl_add_u64 v[96:97], s[10:11], 0, v[182:183]
	v_fmac_f32_e32 v98, v108, v108
	v_fmac_f32_e32 v99, v110, v110
	v_lshl_add_u64 v[126:127], v[96:97], 0, v[174:175]
	v_cvt_pk_bf16_f32 v96, v108, v109
	v_add_f32_e32 v98, v98, v99
	v_mul_f32_e32 v99, v105, v105
	v_mul_f32_e32 v108, v107, v107
	v_fmac_f32_e32 v99, v104, v104
	v_fmac_f32_e32 v108, v106, v106
	v_add_f32_e32 v99, v99, v108
	v_add_f32_e32 v98, v98, v99
	v_mul_f32_e32 v99, v101, v101
	v_mul_f32_e32 v108, v103, v103
	v_fmac_f32_e32 v99, v100, v100
	v_fmac_f32_e32 v108, v102, v102
	v_add_f32_e32 v99, v99, v108
	v_mul_f32_e32 v108, v123, v123
	v_mul_f32_e32 v109, v125, v125
	v_fmac_f32_e32 v108, v122, v122
	v_fmac_f32_e32 v109, v124, v124
	v_add_f32_e32 v108, v108, v109
	v_add_f32_e32 v99, v99, v108
	v_add_f32_e32 v108, v98, v99
	v_mov_b32_e32 v109, v108
	s_nop 1
	v_permlane16_swap_b32_e32 v108, v109
	v_cvt_pk_bf16_f32 v97, v110, v111
	v_cvt_pk_bf16_f32 v98, v104, v105
	v_cvt_pk_bf16_f32 v99, v106, v107
	global_store_dwordx4 v[126:127], v[96:99], off
	s_waitcnt lgkmcnt(0)
	s_nop 0
	v_add_f32_e32 v96, v108, v109
	v_mov_b32_e32 v97, v96
	s_nop 1
	v_permlane32_swap_b32_e32 v96, v97
	v_cvt_pk_bf16_f32 v98, v100, v101
	v_cvt_pk_bf16_f32 v99, v102, v103
	v_cvt_pk_bf16_f32 v100, v122, v123
	v_cvt_pk_bf16_f32 v101, v124, v125
	global_store_dwordx4 v[126:127], v[98:101], off offset:64
	s_and_saveexec_b64 s[24:25], s[4:5]
	s_mov_b32 s30, s72
	s_cbranch_execz .LBB0_888
	s_add_u32 s28, s51, s27
	s_addc_u32 s29, s52, s26
	s_waitcnt lgkmcnt(0)
	v_add_f32_e32 v98, v96, v97
	v_lshl_add_u64 v[96:97], v[170:171], 2, s[28:29]
	global_store_dword v[96:97], v98, off offset:64
.LBB0_888:
	s_or_b64 exec, exec, s[24:25]
	v_or_b32_e32 v96, 32, v178
	s_waitcnt lgkmcnt(0)
	v_ashrrev_i32_e32 v97, 31, v96
	v_lshlrev_b64 v[96:97], 11, v[96:97]
	v_lshl_add_u64 v[96:97], s[10:11], 0, v[96:97]
	v_lshl_add_u64 v[104:105], v[96:97], 0, v[174:175]
	global_load_dwordx4 v[100:103], v[104:105], off
	global_load_dwordx4 v[96:99], v[104:105], off offset:64
	v_lshlrev_b32_e32 v108, 16, v149
	v_and_b32_e32 v109, 0xffff0000, v149
	v_lshlrev_b32_e32 v106, 16, v148
	v_and_b32_e32 v107, 0xffff0000, v148
	v_pk_add_f32 v[94:95], v[94:95], v[108:109]
	v_lshlrev_b32_e32 v108, 16, v151
	v_and_b32_e32 v109, 0xffff0000, v151
	v_pk_add_f32 v[92:93], v[92:93], v[106:107]
	v_lshlrev_b32_e32 v106, 16, v150
	v_and_b32_e32 v107, 0xffff0000, v150
	v_pk_add_f32 v[90:91], v[90:91], v[108:109]
	v_lshlrev_b32_e32 v108, 16, v145
	v_and_b32_e32 v109, 0xffff0000, v145
	v_pk_add_f32 v[88:89], v[88:89], v[106:107]
	v_lshlrev_b32_e32 v106, 16, v144
	v_and_b32_e32 v107, 0xffff0000, v144
	v_pk_add_f32 v[86:87], v[86:87], v[108:109]
	v_lshlrev_b32_e32 v108, 16, v147
	v_and_b32_e32 v109, 0xffff0000, v147
	v_pk_add_f32 v[84:85], v[84:85], v[106:107]
	v_lshlrev_b32_e32 v106, 16, v146
	v_and_b32_e32 v107, 0xffff0000, v146
	v_pk_add_f32 v[108:109], v[82:83], v[108:109]
	v_mul_f32_e32 v82, v93, v93
	v_mul_f32_e32 v83, v95, v95
	v_pk_add_f32 v[106:107], v[80:81], v[106:107]
	v_lshl_add_u64 v[80:81], s[10:11], 0, v[180:181]
	v_fmac_f32_e32 v82, v92, v92
	v_fmac_f32_e32 v83, v94, v94
	v_lshl_add_u64 v[110:111], v[80:81], 0, v[174:175]
	v_cvt_pk_bf16_f32 v80, v92, v93
	v_add_f32_e32 v82, v82, v83
	v_mul_f32_e32 v83, v89, v89
	v_mul_f32_e32 v92, v91, v91
	v_fmac_f32_e32 v83, v88, v88
	v_fmac_f32_e32 v92, v90, v90
	v_add_f32_e32 v83, v83, v92
	v_add_f32_e32 v82, v82, v83
	v_mul_f32_e32 v83, v85, v85
	v_mul_f32_e32 v92, v87, v87
	v_fmac_f32_e32 v83, v84, v84
	v_fmac_f32_e32 v92, v86, v86
	v_add_f32_e32 v83, v83, v92
	v_mul_f32_e32 v92, v107, v107
	v_mul_f32_e32 v93, v109, v109
	v_fmac_f32_e32 v92, v106, v106
	v_fmac_f32_e32 v93, v108, v108
	v_add_f32_e32 v92, v92, v93
	v_add_f32_e32 v83, v83, v92
	v_add_f32_e32 v92, v82, v83
	v_mov_b32_e32 v93, v92
	s_nop 1
	v_permlane16_swap_b32_e32 v92, v93
	v_cvt_pk_bf16_f32 v81, v94, v95
	v_cvt_pk_bf16_f32 v82, v88, v89
	v_cvt_pk_bf16_f32 v83, v90, v91
	global_store_dwordx4 v[110:111], v[80:83], off
	s_waitcnt lgkmcnt(0)
	s_nop 0
	v_add_f32_e32 v80, v92, v93
	v_mov_b32_e32 v81, v80
	s_nop 1
	v_permlane32_swap_b32_e32 v80, v81
	v_cvt_pk_bf16_f32 v82, v84, v85
	v_cvt_pk_bf16_f32 v83, v86, v87
	v_cvt_pk_bf16_f32 v84, v106, v107
	v_cvt_pk_bf16_f32 v85, v108, v109
	global_store_dwordx4 v[110:111], v[82:85], off offset:64
	s_and_saveexec_b64 s[24:25], s[4:5]
	s_cbranch_execz .LBB0_890
	s_add_u32 s28, s51, s27
	s_addc_u32 s29, s52, s26
	s_waitcnt lgkmcnt(0)
	v_add_f32_e32 v82, v80, v81
	v_lshl_add_u64 v[80:81], v[170:171], 2, s[28:29]
	global_store_dword v[80:81], v82, off offset:128
.LBB0_890:
	s_or_b64 exec, exec, s[24:25]
	v_or_b32_e32 v80, 48, v178
	s_waitcnt lgkmcnt(0)
	v_ashrrev_i32_e32 v81, 31, v80
	v_lshlrev_b64 v[80:81], 11, v[80:81]
	v_lshl_add_u64 v[80:81], s[10:11], 0, v[80:81]
	v_lshl_add_u64 v[88:89], v[80:81], 0, v[174:175]
	global_load_dwordx4 v[84:87], v[88:89], off
	global_load_dwordx4 v[80:83], v[88:89], off offset:64
	v_lshlrev_b32_e32 v92, 16, v141
	v_and_b32_e32 v93, 0xffff0000, v141
	v_lshlrev_b32_e32 v90, 16, v140
	v_and_b32_e32 v91, 0xffff0000, v140
	v_pk_add_f32 v[78:79], v[78:79], v[92:93]
	v_lshlrev_b32_e32 v92, 16, v143
	v_and_b32_e32 v93, 0xffff0000, v143
	v_pk_add_f32 v[76:77], v[76:77], v[90:91]
	v_lshlrev_b32_e32 v90, 16, v142
	v_and_b32_e32 v91, 0xffff0000, v142
	v_pk_add_f32 v[74:75], v[74:75], v[92:93]
	s_waitcnt vmcnt(16)
	v_lshlrev_b32_e32 v92, 16, v137
	v_and_b32_e32 v93, 0xffff0000, v137
	v_pk_add_f32 v[72:73], v[72:73], v[90:91]
	v_lshlrev_b32_e32 v90, 16, v136
	v_and_b32_e32 v91, 0xffff0000, v136
	v_pk_add_f32 v[70:71], v[70:71], v[92:93]
	v_lshlrev_b32_e32 v92, 16, v139
	v_and_b32_e32 v93, 0xffff0000, v139
	v_pk_add_f32 v[68:69], v[68:69], v[90:91]
	v_lshlrev_b32_e32 v90, 16, v138
	v_and_b32_e32 v91, 0xffff0000, v138
	v_pk_add_f32 v[92:93], v[66:67], v[92:93]
	v_mul_f32_e32 v66, v77, v77
	v_mul_f32_e32 v67, v79, v79
	v_pk_add_f32 v[90:91], v[64:65], v[90:91]
	v_lshl_add_u64 v[64:65], s[10:11], 0, v[176:177]
	v_fmac_f32_e32 v66, v76, v76
	v_fmac_f32_e32 v67, v78, v78
	v_lshl_add_u64 v[94:95], v[64:65], 0, v[174:175]
	v_cvt_pk_bf16_f32 v64, v76, v77
	v_add_f32_e32 v66, v66, v67
	v_mul_f32_e32 v67, v73, v73
	v_mul_f32_e32 v76, v75, v75
	v_fmac_f32_e32 v67, v72, v72
	v_fmac_f32_e32 v76, v74, v74
	v_add_f32_e32 v67, v67, v76
	v_add_f32_e32 v66, v66, v67
	v_mul_f32_e32 v67, v69, v69
	v_mul_f32_e32 v76, v71, v71
	v_fmac_f32_e32 v67, v68, v68
	v_fmac_f32_e32 v76, v70, v70
	v_add_f32_e32 v67, v67, v76
	v_mul_f32_e32 v76, v91, v91
	v_mul_f32_e32 v77, v93, v93
	v_fmac_f32_e32 v76, v90, v90
	v_fmac_f32_e32 v77, v92, v92
	v_add_f32_e32 v76, v76, v77
	v_add_f32_e32 v67, v67, v76
	v_add_f32_e32 v76, v66, v67
	ds_bpermute_b32 v77, v192, v76
	v_cvt_pk_bf16_f32 v65, v78, v79
	v_cvt_pk_bf16_f32 v66, v72, v73
	v_cvt_pk_bf16_f32 v67, v74, v75
	global_store_dwordx4 v[94:95], v[64:67], off
	s_waitcnt lgkmcnt(0)
	s_nop 0
	v_add_f32_e32 v64, v76, v77
	v_mov_b32_e32 v65, v64
	s_nop 1
	v_permlane32_swap_b32_e32 v64, v65
	v_cvt_pk_bf16_f32 v66, v68, v69
	v_cvt_pk_bf16_f32 v67, v70, v71
	v_cvt_pk_bf16_f32 v68, v90, v91
	v_cvt_pk_bf16_f32 v69, v92, v93
	global_store_dwordx4 v[94:95], v[66:69], off offset:64
	s_and_saveexec_b64 s[24:25], s[4:5]
	s_cbranch_execz .LBB0_892
	s_add_u32 s28, s51, s27
	s_addc_u32 s29, s52, s26
	s_waitcnt lgkmcnt(0)
	v_add_f32_e32 v66, v64, v65
	v_lshl_add_u64 v[64:65], v[170:171], 2, s[28:29]
	global_store_dword v[64:65], v66, off offset:192
.LBB0_892:
	s_or_b64 exec, exec, s[24:25]
	s_waitcnt vmcnt(17)
	v_lshlrev_b32_e32 v66, 16, v133
	v_and_b32_e32 v67, 0xffff0000, v133
	v_pk_add_f32 v[62:63], v[62:63], v[66:67]
	v_lshlrev_b32_e32 v66, 16, v135
	v_and_b32_e32 v67, 0xffff0000, v135
	v_lshlrev_b32_e32 v64, 16, v132
	s_waitcnt lgkmcnt(0)
	v_and_b32_e32 v65, 0xffff0000, v132
	v_pk_add_f32 v[58:59], v[58:59], v[66:67]
	v_lshlrev_b32_e32 v66, 16, v129
	v_and_b32_e32 v67, 0xffff0000, v129
	v_pk_add_f32 v[60:61], v[60:61], v[64:65]
	v_lshlrev_b32_e32 v64, 16, v134
	v_and_b32_e32 v65, 0xffff0000, v134
	v_pk_add_f32 v[54:55], v[54:55], v[66:67]
	v_lshlrev_b32_e32 v66, 16, v131
	v_and_b32_e32 v67, 0xffff0000, v131
	v_pk_add_f32 v[56:57], v[56:57], v[64:65]
	v_lshlrev_b32_e32 v64, 16, v128
	v_and_b32_e32 v65, 0xffff0000, v128
	v_pk_add_f32 v[66:67], v[50:51], v[66:67]
	v_mul_f32_e32 v50, v61, v61
	v_mul_f32_e32 v51, v63, v63
	v_pk_add_f32 v[52:53], v[52:53], v[64:65]
	v_lshlrev_b32_e32 v64, 16, v130
	v_and_b32_e32 v65, 0xffff0000, v130
	v_fmac_f32_e32 v50, v60, v60
	v_fmac_f32_e32 v51, v62, v62
	v_pk_add_f32 v[64:65], v[48:49], v[64:65]
	v_cvt_pk_bf16_f32 v48, v60, v61
	v_add_f32_e32 v50, v50, v51
	v_mul_f32_e32 v51, v57, v57
	v_mul_f32_e32 v60, v59, v59
	v_fmac_f32_e32 v51, v56, v56
	v_fmac_f32_e32 v60, v58, v58
	v_add_f32_e32 v51, v51, v60
	v_add_f32_e32 v50, v50, v51
	v_mul_f32_e32 v51, v53, v53
	v_mul_f32_e32 v60, v55, v55
	v_fmac_f32_e32 v51, v52, v52
	v_fmac_f32_e32 v60, v54, v54
	v_add_f32_e32 v51, v51, v60
	v_mul_f32_e32 v60, v65, v65
	v_mul_f32_e32 v61, v67, v67
	v_fmac_f32_e32 v60, v64, v64
	v_fmac_f32_e32 v61, v66, v66
	v_add_f32_e32 v60, v60, v61
	v_add_f32_e32 v51, v51, v60
	v_add_f32_e32 v60, v50, v51
	ds_bpermute_b32 v61, v192, v60
	v_cvt_pk_bf16_f32 v49, v62, v63
	v_cvt_pk_bf16_f32 v50, v56, v57
	v_cvt_pk_bf16_f32 v51, v58, v59
	global_store_dwordx4 v[172:173], v[48:51], off
	s_waitcnt lgkmcnt(0)
	s_nop 0
	v_add_f32_e32 v48, v60, v61
	v_mov_b32_e32 v49, v48
	s_nop 1
	v_permlane32_swap_b32_e32 v48, v49
	v_cvt_pk_bf16_f32 v50, v52, v53
	v_cvt_pk_bf16_f32 v51, v54, v55
	v_cvt_pk_bf16_f32 v52, v64, v65
	v_cvt_pk_bf16_f32 v53, v66, v67
	global_store_dwordx4 v[172:173], v[50:53], off offset:64
	s_and_saveexec_b64 s[24:25], s[4:5]
	s_cbranch_execz .LBB0_894
	s_add_u32 s28, s51, s27
	s_addc_u32 s29, s52, s26
	s_waitcnt lgkmcnt(0)
	v_add_f32_e32 v50, v48, v49
	v_lshl_add_u64 v[48:49], v[170:171], 2, s[28:29]
	global_store_dword v[48:49], v50, off offset:512
.LBB0_894:
	s_or_b64 exec, exec, s[24:25]
	s_waitcnt vmcnt(13)
	v_lshlrev_b32_e32 v50, 16, v117
	v_and_b32_e32 v51, 0xffff0000, v117
	v_pk_add_f32 v[46:47], v[46:47], v[50:51]
	v_lshlrev_b32_e32 v50, 16, v119
	v_and_b32_e32 v51, 0xffff0000, v119
	v_lshlrev_b32_e32 v48, 16, v116
	s_waitcnt lgkmcnt(0)
	v_and_b32_e32 v49, 0xffff0000, v116
	v_pk_add_f32 v[42:43], v[42:43], v[50:51]
	s_waitcnt vmcnt(12)
	v_lshlrev_b32_e32 v50, 16, v113
	v_and_b32_e32 v51, 0xffff0000, v113
	v_pk_add_f32 v[44:45], v[44:45], v[48:49]
	v_lshlrev_b32_e32 v48, 16, v118
	v_and_b32_e32 v49, 0xffff0000, v118
	v_pk_add_f32 v[38:39], v[38:39], v[50:51]
	v_lshlrev_b32_e32 v50, 16, v115
	v_and_b32_e32 v51, 0xffff0000, v115
	v_pk_add_f32 v[40:41], v[40:41], v[48:49]
	v_lshlrev_b32_e32 v48, 16, v112
	v_and_b32_e32 v49, 0xffff0000, v112
	v_pk_add_f32 v[50:51], v[34:35], v[50:51]
	v_mul_f32_e32 v34, v45, v45
	v_mul_f32_e32 v35, v47, v47
	v_pk_add_f32 v[36:37], v[36:37], v[48:49]
	v_lshlrev_b32_e32 v48, 16, v114
	v_and_b32_e32 v49, 0xffff0000, v114
	v_fmac_f32_e32 v34, v44, v44
	v_fmac_f32_e32 v35, v46, v46
	v_pk_add_f32 v[48:49], v[32:33], v[48:49]
	v_cvt_pk_bf16_f32 v32, v44, v45
	v_add_f32_e32 v34, v34, v35
	v_mul_f32_e32 v35, v41, v41
	v_mul_f32_e32 v44, v43, v43
	v_fmac_f32_e32 v35, v40, v40
	v_fmac_f32_e32 v44, v42, v42
	v_add_f32_e32 v35, v35, v44
	v_add_f32_e32 v34, v34, v35
	v_mul_f32_e32 v35, v37, v37
	v_mul_f32_e32 v44, v39, v39
	v_fmac_f32_e32 v35, v36, v36
	v_fmac_f32_e32 v44, v38, v38
	v_add_f32_e32 v35, v35, v44
	v_mul_f32_e32 v44, v49, v49
	v_mul_f32_e32 v45, v51, v51
	v_fmac_f32_e32 v44, v48, v48
	v_fmac_f32_e32 v45, v50, v50
	v_add_f32_e32 v44, v44, v45
	v_add_f32_e32 v35, v35, v44
	v_add_f32_e32 v44, v34, v35
	ds_bpermute_b32 v45, v192, v44
	v_cvt_pk_bf16_f32 v33, v46, v47
	v_cvt_pk_bf16_f32 v34, v40, v41
	v_cvt_pk_bf16_f32 v35, v42, v43
	global_store_dwordx4 v[120:121], v[32:35], off
	s_waitcnt lgkmcnt(0)
	s_nop 0
	v_add_f32_e32 v32, v44, v45
	v_mov_b32_e32 v33, v32
	s_nop 1
	v_permlane32_swap_b32_e32 v32, v33
	v_cvt_pk_bf16_f32 v34, v36, v37
	v_cvt_pk_bf16_f32 v35, v38, v39
	v_cvt_pk_bf16_f32 v36, v48, v49
	v_cvt_pk_bf16_f32 v37, v50, v51
	global_store_dwordx4 v[120:121], v[34:37], off offset:64
	s_and_saveexec_b64 s[24:25], s[4:5]
	s_cbranch_execz .LBB0_896
	s_add_u32 s28, s51, s27
	s_addc_u32 s29, s52, s26
	s_waitcnt lgkmcnt(0)
	v_add_f32_e32 v34, v32, v33
	v_lshl_add_u64 v[32:33], v[170:171], 2, s[28:29]
	global_store_dword v[32:33], v34, off offset:576
.LBB0_896:
	s_or_b64 exec, exec, s[24:25]
	s_waitcnt vmcnt(11)
	v_lshlrev_b32_e32 v34, 16, v101
	v_and_b32_e32 v35, 0xffff0000, v101
	v_pk_add_f32 v[30:31], v[30:31], v[34:35]
	v_lshlrev_b32_e32 v34, 16, v103
	v_and_b32_e32 v35, 0xffff0000, v103
	v_lshlrev_b32_e32 v32, 16, v100
	s_waitcnt lgkmcnt(0)
	v_and_b32_e32 v33, 0xffff0000, v100
	v_pk_add_f32 v[26:27], v[26:27], v[34:35]
	s_waitcnt vmcnt(10)
	v_lshlrev_b32_e32 v34, 16, v97
	v_and_b32_e32 v35, 0xffff0000, v97
	v_pk_add_f32 v[28:29], v[28:29], v[32:33]
	v_lshlrev_b32_e32 v32, 16, v102
	v_and_b32_e32 v33, 0xffff0000, v102
	v_pk_add_f32 v[22:23], v[22:23], v[34:35]
	v_lshlrev_b32_e32 v34, 16, v99
	v_and_b32_e32 v35, 0xffff0000, v99
	v_pk_add_f32 v[24:25], v[24:25], v[32:33]
	v_lshlrev_b32_e32 v32, 16, v96
	v_and_b32_e32 v33, 0xffff0000, v96
	v_pk_add_f32 v[34:35], v[18:19], v[34:35]
	v_mul_f32_e32 v18, v29, v29
	v_mul_f32_e32 v19, v31, v31
	v_pk_add_f32 v[20:21], v[20:21], v[32:33]
	v_lshlrev_b32_e32 v32, 16, v98
	v_and_b32_e32 v33, 0xffff0000, v98
	v_fmac_f32_e32 v18, v28, v28
	v_fmac_f32_e32 v19, v30, v30
	v_pk_add_f32 v[32:33], v[16:17], v[32:33]
	v_cvt_pk_bf16_f32 v16, v28, v29
	v_add_f32_e32 v18, v18, v19
	v_mul_f32_e32 v19, v25, v25
	v_mul_f32_e32 v28, v27, v27
	v_fmac_f32_e32 v19, v24, v24
	v_fmac_f32_e32 v28, v26, v26
	v_add_f32_e32 v19, v19, v28
	v_add_f32_e32 v18, v18, v19
	v_mul_f32_e32 v19, v21, v21
	v_mul_f32_e32 v28, v23, v23
	v_fmac_f32_e32 v19, v20, v20
	v_fmac_f32_e32 v28, v22, v22
	v_add_f32_e32 v19, v19, v28
	v_mul_f32_e32 v28, v33, v33
	v_mul_f32_e32 v29, v35, v35
	v_fmac_f32_e32 v28, v32, v32
	v_fmac_f32_e32 v29, v34, v34
	v_add_f32_e32 v28, v28, v29
	v_add_f32_e32 v19, v19, v28
	v_add_f32_e32 v28, v18, v19
	ds_bpermute_b32 v29, v192, v28
	v_cvt_pk_bf16_f32 v17, v30, v31
	v_cvt_pk_bf16_f32 v18, v24, v25
	v_cvt_pk_bf16_f32 v19, v26, v27
	global_store_dwordx4 v[104:105], v[16:19], off
	s_waitcnt lgkmcnt(0)
	s_nop 0
	v_add_f32_e32 v16, v28, v29
	v_mov_b32_e32 v17, v16
	s_nop 1
	v_permlane32_swap_b32_e32 v16, v17
	v_cvt_pk_bf16_f32 v18, v20, v21
	v_cvt_pk_bf16_f32 v19, v22, v23
	v_cvt_pk_bf16_f32 v20, v32, v33
	v_cvt_pk_bf16_f32 v21, v34, v35
	global_store_dwordx4 v[104:105], v[18:21], off offset:64
	s_and_saveexec_b64 s[24:25], s[4:5]
	s_cbranch_execz .LBB0_898
	s_add_u32 s28, s51, s27
	s_addc_u32 s29, s52, s26
	s_waitcnt lgkmcnt(0)
	v_add_f32_e32 v18, v16, v17
	v_lshl_add_u64 v[16:17], v[170:171], 2, s[28:29]
	global_store_dword v[16:17], v18, off offset:640
.LBB0_898:
	s_or_b64 exec, exec, s[24:25]
	s_waitcnt vmcnt(9)
	v_lshlrev_b32_e32 v18, 16, v85
	v_and_b32_e32 v19, 0xffff0000, v85
	v_pk_add_f32 v[14:15], v[14:15], v[18:19]
	v_lshlrev_b32_e32 v18, 16, v87
	v_and_b32_e32 v19, 0xffff0000, v87
	v_lshlrev_b32_e32 v16, 16, v84
	s_waitcnt lgkmcnt(0)
	v_and_b32_e32 v17, 0xffff0000, v84
	v_pk_add_f32 v[10:11], v[10:11], v[18:19]
	s_waitcnt vmcnt(8)
	v_lshlrev_b32_e32 v18, 16, v81
	v_and_b32_e32 v19, 0xffff0000, v81
	v_pk_add_f32 v[12:13], v[12:13], v[16:17]
	v_lshlrev_b32_e32 v16, 16, v86
	v_and_b32_e32 v17, 0xffff0000, v86
	v_pk_add_f32 v[6:7], v[6:7], v[18:19]
	v_lshlrev_b32_e32 v18, 16, v83
	v_and_b32_e32 v19, 0xffff0000, v83
	v_pk_add_f32 v[8:9], v[8:9], v[16:17]
	v_lshlrev_b32_e32 v16, 16, v80
	v_and_b32_e32 v17, 0xffff0000, v80
	v_pk_add_f32 v[18:19], v[2:3], v[18:19]
	v_mul_f32_e32 v2, v13, v13
	v_mul_f32_e32 v3, v15, v15
	v_pk_add_f32 v[4:5], v[4:5], v[16:17]
	v_lshlrev_b32_e32 v16, 16, v82
	v_and_b32_e32 v17, 0xffff0000, v82
	v_fmac_f32_e32 v2, v12, v12
	v_fmac_f32_e32 v3, v14, v14
	v_pk_add_f32 v[16:17], v[0:1], v[16:17]
	v_cvt_pk_bf16_f32 v0, v12, v13
	v_add_f32_e32 v2, v2, v3
	v_mul_f32_e32 v3, v9, v9
	v_mul_f32_e32 v12, v11, v11
	v_fmac_f32_e32 v3, v8, v8
	v_fmac_f32_e32 v12, v10, v10
	v_add_f32_e32 v3, v3, v12
	v_add_f32_e32 v2, v2, v3
	v_mul_f32_e32 v3, v5, v5
	v_mul_f32_e32 v12, v7, v7
	v_fmac_f32_e32 v3, v4, v4
	v_fmac_f32_e32 v12, v6, v6
	v_add_f32_e32 v3, v3, v12
	v_mul_f32_e32 v12, v17, v17
	v_mul_f32_e32 v13, v19, v19
	v_fmac_f32_e32 v12, v16, v16
	v_fmac_f32_e32 v13, v18, v18
	v_add_f32_e32 v12, v12, v13
	v_add_f32_e32 v3, v3, v12
	v_add_f32_e32 v12, v2, v3
	v_mov_b32_e32 v13, v12
	s_nop 1
	v_permlane16_swap_b32_e32 v12, v13
	v_cvt_pk_bf16_f32 v1, v14, v15
	v_cvt_pk_bf16_f32 v2, v8, v9
	v_cvt_pk_bf16_f32 v3, v10, v11
	global_store_dwordx4 v[88:89], v[0:3], off
	s_waitcnt lgkmcnt(0)
	s_nop 0
	v_add_f32_e32 v0, v12, v13
	v_mov_b32_e32 v1, v0
	s_nop 1
	v_permlane32_swap_b32_e32 v0, v1
	v_cvt_pk_bf16_f32 v2, v4, v5
	v_cvt_pk_bf16_f32 v3, v6, v7
	v_cvt_pk_bf16_f32 v4, v16, v17
	v_cvt_pk_bf16_f32 v5, v18, v19
	global_store_dwordx4 v[88:89], v[2:5], off offset:64
	s_and_saveexec_b64 s[24:25], s[4:5]
	s_cbranch_execz .LBB0_877
	s_add_u32 s28, s51, s27
	s_addc_u32 s29, s52, s26
	s_waitcnt lgkmcnt(0)
	v_add_f32_e32 v2, v0, v1
	v_lshl_add_u64 v[0:1], v[170:171], 2, s[28:29]
	global_store_dword v[0:1], v2, off offset:704
	s_branch .LBB0_877

.LBB0_1128:
	ds_read_b128 v[128:131], v186
	ds_read_b128 v[132:135], v186 offset:1024
	ds_read_b128 v[136:139], v186 offset:2048
	ds_read_b128 v[140:143], v186 offset:3072
	s_add_u32 s26, s24, 0xfffe0080
	s_addc_u32 s27, s25, -1
	s_cmp_eq_u32 s38, 4
	s_cselect_b32 s29, s19, s27
	s_cselect_b32 s28, s30, s26
	s_cselect_b32 s27, s34, s37
	s_cselect_b32 s26, s35, s36
	v_lshl_add_u64 v[182:183], s[24:25], 0, v[164:165]
	s_add_i32 m0, s42, 0xc000
	ds_read_b128 v[144:147], v187
	ds_read_b128 v[148:151], v187 offset:1024
	ds_read_b128 v[152:155], v187 offset:2048
	ds_read_b128 v[156:159], v187 offset:3072
	ds_read_b128 v[170:173], v187 offset:4096
	ds_read_b128 v[174:177], v187 offset:5120
	ds_read_b128 v[178:181], v187 offset:6144
	ds_read_b128 v[192:195], v187 offset:7168
	global_load_lds_dwordx4 v[182:183], off
	v_lshl_add_u64 v[182:183], s[24:25], 0, v[166:167]
	s_add_i32 m0, s42, 0xe000
	s_nop 0
	global_load_lds_dwordx4 v[182:183], off
	ds_read_b128 v[196:199], v188
	ds_read_b128 v[204:207], v188 offset:1024
	ds_read_b128 v[208:211], v188 offset:2048
	ds_read_b128 v[212:215], v188 offset:3072
	s_waitcnt lgkmcnt(0)
	s_waitcnt vmcnt(8)
	s_barrier
	s_setprio 1
	v_mfma_f32_16x16x32_bf16 v[124:127], v[128:131], v[144:147], v[124:127]
	v_mfma_f32_16x16x32_bf16 v[120:123], v[136:139], v[144:147], v[120:123]
	v_mfma_f32_16x16x32_bf16 v[108:111], v[128:131], v[152:155], v[108:111]
	v_mfma_f32_16x16x32_bf16 v[104:107], v[136:139], v[152:155], v[104:107]
	v_mfma_f32_16x16x32_bf16 v[92:95], v[128:131], v[170:173], v[92:95]
	v_mfma_f32_16x16x32_bf16 v[88:91], v[136:139], v[170:173], v[88:91]
	v_mfma_f32_16x16x32_bf16 v[76:79], v[128:131], v[178:181], v[76:79]
	v_mfma_f32_16x16x32_bf16 v[72:75], v[136:139], v[178:181], v[72:75]
	v_mfma_f32_16x16x32_bf16 v[124:127], v[132:135], v[148:151], v[124:127]
	v_mfma_f32_16x16x32_bf16 v[120:123], v[140:143], v[148:151], v[120:123]
	v_mfma_f32_16x16x32_bf16 v[108:111], v[132:135], v[156:159], v[108:111]
	v_mfma_f32_16x16x32_bf16 v[104:107], v[140:143], v[156:159], v[104:107]
	v_mfma_f32_16x16x32_bf16 v[92:95], v[132:135], v[174:177], v[92:95]
	v_mfma_f32_16x16x32_bf16 v[88:91], v[140:143], v[174:177], v[88:91]
	v_mfma_f32_16x16x32_bf16 v[76:79], v[132:135], v[192:195], v[76:79]
	v_mfma_f32_16x16x32_bf16 v[72:75], v[140:143], v[192:195], v[72:75]
	v_mfma_f32_16x16x32_bf16 v[116:119], v[196:199], v[144:147], v[116:119]
	v_mfma_f32_16x16x32_bf16 v[112:115], v[208:211], v[144:147], v[112:115]
	v_mfma_f32_16x16x32_bf16 v[100:103], v[196:199], v[152:155], v[100:103]
	v_mfma_f32_16x16x32_bf16 v[96:99], v[208:211], v[152:155], v[96:99]
	v_mfma_f32_16x16x32_bf16 v[84:87], v[196:199], v[170:173], v[84:87]
	v_mfma_f32_16x16x32_bf16 v[80:83], v[208:211], v[170:173], v[80:83]
	v_mfma_f32_16x16x32_bf16 v[68:71], v[196:199], v[178:181], v[68:71]
	v_mfma_f32_16x16x32_bf16 v[64:67], v[208:211], v[178:181], v[64:67]
	v_mfma_f32_16x16x32_bf16 v[116:119], v[204:207], v[148:151], v[116:119]
	v_mfma_f32_16x16x32_bf16 v[112:115], v[212:215], v[148:151], v[112:115]
	v_mfma_f32_16x16x32_bf16 v[100:103], v[204:207], v[156:159], v[100:103]
	v_mfma_f32_16x16x32_bf16 v[96:99], v[212:215], v[156:159], v[96:99]
	v_mfma_f32_16x16x32_bf16 v[84:87], v[204:207], v[174:177], v[84:87]
	v_mfma_f32_16x16x32_bf16 v[80:83], v[212:215], v[174:177], v[80:83]
	v_mfma_f32_16x16x32_bf16 v[68:71], v[204:207], v[192:195], v[68:71]
	v_mfma_f32_16x16x32_bf16 v[64:67], v[212:215], v[192:195], v[64:67]
	s_setprio 0
	s_barrier
	ds_read_b128 v[144:147], v187 offset:16384
	ds_read_b128 v[148:151], v187 offset:17408
	ds_read_b128 v[152:155], v187 offset:18432
	ds_read_b128 v[156:159], v187 offset:19456
	ds_read_b128 v[170:173], v187 offset:20480
	ds_read_b128 v[174:177], v187 offset:21504
	ds_read_b128 v[178:181], v187 offset:22528
	ds_read_b128 v[192:195], v187 offset:23552
	s_mov_b32 m0, s40
	v_lshl_add_u64 v[182:183], s[26:27], 0, v[160:161]
	global_load_lds_dwordx4 v[182:183], off
	v_lshl_add_u64 v[200:201], s[26:27], 0, v[162:163]
	s_mov_b32 m0, s41
	s_nop 0
	global_load_lds_dwordx4 v[200:201], off
	s_mov_b32 m0, s42
	v_lshl_add_u64 v[216:217], s[28:29], 0, v[160:161]
	global_load_lds_dwordx4 v[216:217], off
	v_lshl_add_u64 v[218:219], s[28:29], 0, v[162:163]
	s_mov_b32 m0, s43
	s_nop 0
	global_load_lds_dwordx4 v[218:219], off
	s_add_u32 s64, s26, 0x20000
	s_addc_u32 s65, s27, 0
	s_mov_b32 m0, s44
	v_lshl_add_u64 v[248:249], s[64:65], 0, v[160:161]
	global_load_lds_dwordx4 v[248:249], off
	v_lshl_add_u64 v[248:249], s[64:65], 0, v[162:163]
	s_mov_b32 m0, s45
	s_nop 0
	global_load_lds_dwordx4 v[248:249], off
	s_waitcnt lgkmcnt(0)
	s_waitcnt vmcnt(8)
	s_barrier
	s_setprio 1
	v_mfma_f32_16x16x32_bf16 v[60:63], v[128:131], v[144:147], v[60:63]
	v_mfma_f32_16x16x32_bf16 v[56:59], v[136:139], v[144:147], v[56:59]
	v_mfma_f32_16x16x32_bf16 v[44:47], v[128:131], v[152:155], v[44:47]
	v_mfma_f32_16x16x32_bf16 v[40:43], v[136:139], v[152:155], v[40:43]
	v_mfma_f32_16x16x32_bf16 v[28:31], v[128:131], v[170:173], v[28:31]
	v_mfma_f32_16x16x32_bf16 v[24:27], v[136:139], v[170:173], v[24:27]
	v_mfma_f32_16x16x32_bf16 v[12:15], v[128:131], v[178:181], v[12:15]
	v_mfma_f32_16x16x32_bf16 v[8:11], v[136:139], v[178:181], v[8:11]
	v_mfma_f32_16x16x32_bf16 v[60:63], v[132:135], v[148:151], v[60:63]
	v_mfma_f32_16x16x32_bf16 v[56:59], v[140:143], v[148:151], v[56:59]
	v_mfma_f32_16x16x32_bf16 v[44:47], v[132:135], v[156:159], v[44:47]
	v_mfma_f32_16x16x32_bf16 v[40:43], v[140:143], v[156:159], v[40:43]
	v_mfma_f32_16x16x32_bf16 v[28:31], v[132:135], v[174:177], v[28:31]
	v_mfma_f32_16x16x32_bf16 v[24:27], v[140:143], v[174:177], v[24:27]
	v_mfma_f32_16x16x32_bf16 v[12:15], v[132:135], v[192:195], v[12:15]
	v_mfma_f32_16x16x32_bf16 v[8:11], v[140:143], v[192:195], v[8:11]
	v_mfma_f32_16x16x32_bf16 v[52:55], v[196:199], v[144:147], v[52:55]
	v_mfma_f32_16x16x32_bf16 v[48:51], v[208:211], v[144:147], v[48:51]
	v_mfma_f32_16x16x32_bf16 v[36:39], v[196:199], v[152:155], v[36:39]
	v_mfma_f32_16x16x32_bf16 v[32:35], v[208:211], v[152:155], v[32:35]
	v_mfma_f32_16x16x32_bf16 v[20:23], v[196:199], v[170:173], v[20:23]
	v_mfma_f32_16x16x32_bf16 v[16:19], v[208:211], v[170:173], v[16:19]
	v_mfma_f32_16x16x32_bf16 v[4:7], v[196:199], v[178:181], v[4:7]
	v_mfma_f32_16x16x32_bf16 v[0:3], v[208:211], v[178:181], v[0:3]
	v_mfma_f32_16x16x32_bf16 v[52:55], v[204:207], v[148:151], v[52:55]
	v_mfma_f32_16x16x32_bf16 v[48:51], v[212:215], v[148:151], v[48:51]
	v_mfma_f32_16x16x32_bf16 v[36:39], v[204:207], v[156:159], v[36:39]
	v_mfma_f32_16x16x32_bf16 v[32:35], v[212:215], v[156:159], v[32:35]
	v_mfma_f32_16x16x32_bf16 v[20:23], v[204:207], v[174:177], v[20:23]
	v_mfma_f32_16x16x32_bf16 v[16:19], v[212:215], v[174:177], v[16:19]
	v_mfma_f32_16x16x32_bf16 v[4:7], v[204:207], v[192:195], v[4:7]
	v_mfma_f32_16x16x32_bf16 v[0:3], v[212:215], v[192:195], v[0:3]
	s_setprio 0
	s_barrier
	ds_read_b128 v[128:131], v189
	ds_read_b128 v[132:135], v189 offset:1024
	ds_read_b128 v[136:139], v189 offset:2048
	ds_read_b128 v[140:143], v189 offset:3072
	s_add_u32 s28, s28, 0x20000
	s_addc_u32 s29, s29, 0
	s_mov_b32 m0, s46
	v_lshl_add_u64 v[196:197], s[28:29], 0, v[160:161]
	ds_read_b128 v[144:147], v187 offset:32768
	ds_read_b128 v[148:151], v187 offset:33792
	ds_read_b128 v[152:155], v187 offset:34816
	ds_read_b128 v[156:159], v187 offset:35840
	ds_read_b128 v[170:173], v187 offset:36864
	ds_read_b128 v[174:177], v187 offset:37888
	ds_read_b128 v[178:181], v187 offset:38912
	ds_read_b128 v[192:195], v187 offset:39936
	global_load_lds_dwordx4 v[196:197], off
	v_lshl_add_u64 v[196:197], s[28:29], 0, v[162:163]
	s_mov_b32 m0, s47
	s_nop 0
	global_load_lds_dwordx4 v[196:197], off
	ds_read_b128 v[196:199], v190
	ds_read_b128 v[204:207], v190 offset:1024
	ds_read_b128 v[208:211], v190 offset:2048
	ds_read_b128 v[212:215], v190 offset:3072
	s_waitcnt lgkmcnt(0)
	s_waitcnt vmcnt(8)
	s_barrier
	s_setprio 1
	v_mfma_f32_16x16x32_bf16 v[124:127], v[128:131], v[144:147], v[124:127]
	v_mfma_f32_16x16x32_bf16 v[120:123], v[136:139], v[144:147], v[120:123]
	v_mfma_f32_16x16x32_bf16 v[108:111], v[128:131], v[152:155], v[108:111]
	v_mfma_f32_16x16x32_bf16 v[104:107], v[136:139], v[152:155], v[104:107]
	v_mfma_f32_16x16x32_bf16 v[92:95], v[128:131], v[170:173], v[92:95]
	v_mfma_f32_16x16x32_bf16 v[88:91], v[136:139], v[170:173], v[88:91]
	v_mfma_f32_16x16x32_bf16 v[76:79], v[128:131], v[178:181], v[76:79]
	v_mfma_f32_16x16x32_bf16 v[72:75], v[136:139], v[178:181], v[72:75]
	v_mfma_f32_16x16x32_bf16 v[124:127], v[132:135], v[148:151], v[124:127]
	v_mfma_f32_16x16x32_bf16 v[120:123], v[140:143], v[148:151], v[120:123]
	v_mfma_f32_16x16x32_bf16 v[108:111], v[132:135], v[156:159], v[108:111]
	v_mfma_f32_16x16x32_bf16 v[104:107], v[140:143], v[156:159], v[104:107]
	v_mfma_f32_16x16x32_bf16 v[92:95], v[132:135], v[174:177], v[92:95]
	v_mfma_f32_16x16x32_bf16 v[88:91], v[140:143], v[174:177], v[88:91]
	v_mfma_f32_16x16x32_bf16 v[76:79], v[132:135], v[192:195], v[76:79]
	v_mfma_f32_16x16x32_bf16 v[72:75], v[140:143], v[192:195], v[72:75]
	v_mfma_f32_16x16x32_bf16 v[116:119], v[196:199], v[144:147], v[116:119]
	v_mfma_f32_16x16x32_bf16 v[112:115], v[208:211], v[144:147], v[112:115]
	v_mfma_f32_16x16x32_bf16 v[100:103], v[196:199], v[152:155], v[100:103]
	v_mfma_f32_16x16x32_bf16 v[96:99], v[208:211], v[152:155], v[96:99]
	v_mfma_f32_16x16x32_bf16 v[84:87], v[196:199], v[170:173], v[84:87]
	v_mfma_f32_16x16x32_bf16 v[80:83], v[208:211], v[170:173], v[80:83]
	v_mfma_f32_16x16x32_bf16 v[68:71], v[196:199], v[178:181], v[68:71]
	v_mfma_f32_16x16x32_bf16 v[64:67], v[208:211], v[178:181], v[64:67]
	v_mfma_f32_16x16x32_bf16 v[116:119], v[204:207], v[148:151], v[116:119]
	v_mfma_f32_16x16x32_bf16 v[112:115], v[212:215], v[148:151], v[112:115]
	v_mfma_f32_16x16x32_bf16 v[100:103], v[204:207], v[156:159], v[100:103]
	v_mfma_f32_16x16x32_bf16 v[96:99], v[212:215], v[156:159], v[96:99]
	v_mfma_f32_16x16x32_bf16 v[84:87], v[204:207], v[174:177], v[84:87]
	v_mfma_f32_16x16x32_bf16 v[80:83], v[212:215], v[174:177], v[80:83]
	v_mfma_f32_16x16x32_bf16 v[68:71], v[204:207], v[192:195], v[68:71]
	v_mfma_f32_16x16x32_bf16 v[64:67], v[212:215], v[192:195], v[64:67]
	s_setprio 0
	s_barrier
	ds_read_b128 v[144:147], v187 offset:49152
	ds_read_b128 v[148:151], v187 offset:50176
	ds_read_b128 v[152:155], v187 offset:51200
	ds_read_b128 v[156:159], v187 offset:52224
	ds_read_b128 v[170:173], v187 offset:53248
	ds_read_b128 v[174:177], v187 offset:54272
	ds_read_b128 v[178:181], v187 offset:55296
	ds_read_b128 v[192:195], v187 offset:56320
	s_mov_b32 m0, s51
	v_lshl_add_u64 v[182:183], v[182:183], 0, s[10:11]
	global_load_lds_dwordx4 v[182:183], off
	v_lshl_add_u64 v[182:183], v[200:201], 0, s[10:11]
	s_mov_b32 m0, s52
	s_nop 0
	global_load_lds_dwordx4 v[182:183], off
	s_mov_b32 m0, s53
	v_lshl_add_u64 v[182:183], v[216:217], 0, s[10:11]
	global_load_lds_dwordx4 v[182:183], off
	v_lshl_add_u64 v[182:183], v[218:219], 0, s[10:11]
	s_mov_b32 m0, s54
	s_nop 0
	global_load_lds_dwordx4 v[182:183], off
	s_add_u32 s26, s26, 0x20080
	s_addc_u32 s27, s27, 0
	s_mov_b32 m0, s55
	v_lshl_add_u64 v[248:249], s[26:27], 0, v[160:161]
	global_load_lds_dwordx4 v[248:249], off
	v_lshl_add_u64 v[248:249], s[26:27], 0, v[162:163]
	s_mov_b32 m0, s56
	s_nop 0
	global_load_lds_dwordx4 v[248:249], off
	s_waitcnt lgkmcnt(0)
	s_waitcnt vmcnt(8)
	s_barrier
	s_setprio 1
	v_mfma_f32_16x16x32_bf16 v[60:63], v[128:131], v[144:147], v[60:63]
	v_mfma_f32_16x16x32_bf16 v[56:59], v[136:139], v[144:147], v[56:59]
	v_mfma_f32_16x16x32_bf16 v[44:47], v[128:131], v[152:155], v[44:47]
	v_mfma_f32_16x16x32_bf16 v[40:43], v[136:139], v[152:155], v[40:43]
	v_mfma_f32_16x16x32_bf16 v[28:31], v[128:131], v[170:173], v[28:31]
	v_mfma_f32_16x16x32_bf16 v[24:27], v[136:139], v[170:173], v[24:27]
	v_mfma_f32_16x16x32_bf16 v[12:15], v[128:131], v[178:181], v[12:15]
	v_mfma_f32_16x16x32_bf16 v[8:11], v[136:139], v[178:181], v[8:11]
	v_mfma_f32_16x16x32_bf16 v[60:63], v[132:135], v[148:151], v[60:63]
	v_mfma_f32_16x16x32_bf16 v[56:59], v[140:143], v[148:151], v[56:59]
	v_mfma_f32_16x16x32_bf16 v[44:47], v[132:135], v[156:159], v[44:47]
	v_mfma_f32_16x16x32_bf16 v[40:43], v[140:143], v[156:159], v[40:43]
	v_mfma_f32_16x16x32_bf16 v[28:31], v[132:135], v[174:177], v[28:31]
	v_mfma_f32_16x16x32_bf16 v[24:27], v[140:143], v[174:177], v[24:27]
	v_mfma_f32_16x16x32_bf16 v[12:15], v[132:135], v[192:195], v[12:15]
	v_mfma_f32_16x16x32_bf16 v[8:11], v[140:143], v[192:195], v[8:11]
	v_mfma_f32_16x16x32_bf16 v[52:55], v[196:199], v[144:147], v[52:55]
	v_mfma_f32_16x16x32_bf16 v[48:51], v[208:211], v[144:147], v[48:51]
	v_mfma_f32_16x16x32_bf16 v[36:39], v[196:199], v[152:155], v[36:39]
	v_mfma_f32_16x16x32_bf16 v[32:35], v[208:211], v[152:155], v[32:35]
	v_mfma_f32_16x16x32_bf16 v[20:23], v[196:199], v[170:173], v[20:23]
	v_mfma_f32_16x16x32_bf16 v[16:19], v[208:211], v[170:173], v[16:19]
	v_mfma_f32_16x16x32_bf16 v[4:7], v[196:199], v[178:181], v[4:7]
	v_mfma_f32_16x16x32_bf16 v[0:3], v[208:211], v[178:181], v[0:3]
	v_mfma_f32_16x16x32_bf16 v[52:55], v[204:207], v[148:151], v[52:55]
	v_mfma_f32_16x16x32_bf16 v[48:51], v[212:215], v[148:151], v[48:51]
	v_mfma_f32_16x16x32_bf16 v[36:39], v[204:207], v[156:159], v[36:39]
	v_mfma_f32_16x16x32_bf16 v[32:35], v[212:215], v[156:159], v[32:35]
	v_mfma_f32_16x16x32_bf16 v[20:23], v[204:207], v[174:177], v[20:23]
	v_mfma_f32_16x16x32_bf16 v[16:19], v[212:215], v[174:177], v[16:19]
	v_mfma_f32_16x16x32_bf16 v[4:7], v[204:207], v[192:195], v[4:7]
	v_mfma_f32_16x16x32_bf16 v[0:3], v[212:215], v[192:195], v[0:3]
	s_setprio 0
	s_add_i32 s38, s38, 2
	s_add_u32 s24, s24, 0x100
	s_addc_u32 s25, s25, 0
	s_add_u32 s36, s36, 0x100
	s_addc_u32 s37, s37, 0
	s_cmp_gt_u32 s38, 5
	s_barrier
	s_cbranch_scc0 .LBB0_1128
	v_lshl_or_b32 v128, s63, 8, v185
	v_lshl_add_u32 v170, s18, 8, v184
	v_ashrrev_i32_e32 v129, 31, v128
	v_lshlrev_b64 v[174:175], 1, v[128:129]
	v_ashrrev_i32_e32 v171, 31, v170
	v_lshl_add_u64 v[128:129], s[8:9], 0, v[174:175]
	v_lshlrev_b64 v[204:205], 11, v[170:171]
	v_lshl_add_u64 v[130:131], v[128:129], 0, v[204:205]
	v_mov_b32_e32 v194, v220
	v_mov_b32_e32 v195, v221
	v_mov_b32_e32 v196, v222
	v_mov_b32_e32 v197, v223
	v_mov_b32_e32 v198, v224
	v_mov_b32_e32 v199, v225
	v_mov_b32_e32 v200, v226
	v_mov_b32_e32 v201, v227
	v_or_b32_e32 v130, 16, v170
	v_or_b32_e32 v132, 32, v170
	v_or_b32_e32 v134, 48, v170
	v_ashrrev_i32_e32 v131, 31, v130
	v_ashrrev_i32_e32 v133, 31, v132
	v_ashrrev_i32_e32 v135, 31, v134
	v_lshlrev_b64 v[182:183], 11, v[130:131]
	v_add_u32_e32 v178, 0x80, v170
	v_lshlrev_b64 v[180:181], 11, v[132:133]
	v_lshlrev_b64 v[176:177], 11, v[134:135]
	v_lshl_add_u64 v[132:133], v[128:129], 0, v[182:183]
	v_ashrrev_i32_e32 v179, 31, v178
	v_lshl_add_u64 v[134:135], v[128:129], 0, v[180:181]
	v_lshl_add_u64 v[128:129], v[128:129], 0, v[176:177]
	v_mov_b32_e32 v156, v228
	v_mov_b32_e32 v157, v229
	v_mov_b32_e32 v158, v230
	v_mov_b32_e32 v159, v231
	v_mov_b32_e32 v152, v232
	v_mov_b32_e32 v153, v233
	v_mov_b32_e32 v154, v234
	v_mov_b32_e32 v155, v235
	v_mov_b32_e32 v148, v236
	v_mov_b32_e32 v149, v237
	v_mov_b32_e32 v150, v238
	v_mov_b32_e32 v151, v239
	v_mov_b32_e32 v144, v240
	v_mov_b32_e32 v145, v241
	v_mov_b32_e32 v146, v242
	v_mov_b32_e32 v147, v243
	v_mov_b32_e32 v140, v252
	v_mov_b32_e32 v141, v253
	v_mov_b32_e32 v142, v254
	v_mov_b32_e32 v143, v255
	global_load_dwordx4 v[136:139], v[128:129], off offset:64
	v_lshlrev_b64 v[130:131], 11, v[178:179]
	v_lshl_add_u64 v[130:131], s[8:9], 0, v[130:131]
	v_lshl_add_u64 v[172:173], v[130:131], 0, v[174:175]
	global_load_dwordx4 v[132:135], v[172:173], off
	global_load_dwordx4 v[128:131], v[172:173], off offset:64
	v_and_b32_e32 v192, 64, v191
	v_xor_b32_e32 v179, 16, v191
	v_add_u32_e32 v192, 64, v192
	v_xor_b32_e32 v193, 32, v191
	v_cmp_lt_i32_e32 vcc, v179, v192
	v_lshl_add_u64 v[204:205], s[8:9], 0, v[204:205]
	v_lshl_add_u64 v[204:205], v[204:205], 0, v[174:175]
	v_cndmask_b32_e32 v179, v191, v179, vcc
	v_cmp_lt_i32_e32 vcc, v193, v192
	v_lshlrev_b32_e32 v192, 2, v179
	s_lshl_b32 s18, s63, 2
	v_cndmask_b32_e32 v193, v191, v193, vcc
	v_lshlrev_b32_e32 v179, 2, v193
	s_or_b32 s25, s18, s50
	s_mul_hi_i32 s24, s25, 0x21000
	s_mul_i32 s25, s25, 0x21000
	v_lshlrev_b32_e32 v206, 16, v194
	v_and_b32_e32 v207, 0xffff0000, v194
	v_lshlrev_b32_e32 v194, 16, v195
	v_and_b32_e32 v195, 0xffff0000, v195
	v_lshlrev_b32_e32 v208, 16, v196
	v_and_b32_e32 v209, 0xffff0000, v196
	v_lshlrev_b32_e32 v196, 16, v197
	v_and_b32_e32 v197, 0xffff0000, v197
	v_lshlrev_b32_e32 v212, 16, v200
	v_and_b32_e32 v213, 0xffff0000, v200
	v_lshlrev_b32_e32 v200, 16, v201
	v_and_b32_e32 v201, 0xffff0000, v201
	v_pk_add_f32 v[126:127], v[126:127], v[194:195]
	v_pk_add_f32 v[124:125], v[124:125], v[206:207]
	v_pk_add_f32 v[122:123], v[122:123], v[196:197]
	v_pk_add_f32 v[120:121], v[120:121], v[208:209]
	v_lshlrev_b32_e32 v210, 16, v198
	v_and_b32_e32 v211, 0xffff0000, v198
	v_lshlrev_b32_e32 v198, 16, v199
	v_and_b32_e32 v199, 0xffff0000, v199
	v_pk_add_f32 v[194:195], v[114:115], v[200:201]
	v_pk_add_f32 v[196:197], v[112:113], v[212:213]
	v_cvt_pk_bf16_f32 v112, v124, v125
	v_cvt_pk_bf16_f32 v113, v126, v127
	v_mul_f32_e32 v114, v125, v125
	v_mul_f32_e32 v115, v127, v127
	v_mul_f32_e32 v125, v121, v121
	v_mul_f32_e32 v127, v123, v123
	v_pk_add_f32 v[118:119], v[118:119], v[198:199]
	v_pk_add_f32 v[116:117], v[116:117], v[210:211]
	v_fmac_f32_e32 v114, v124, v124
	v_fmac_f32_e32 v115, v126, v126
	v_fmac_f32_e32 v125, v120, v120
	v_fmac_f32_e32 v127, v122, v122
	v_mul_f32_e32 v193, v117, v117
	v_mul_f32_e32 v198, v119, v119
	v_add_f32_e32 v114, v114, v115
	v_add_f32_e32 v115, v125, v127
	v_mul_f32_e32 v124, v197, v197
	v_mul_f32_e32 v125, v195, v195
	v_fmac_f32_e32 v193, v116, v116
	v_fmac_f32_e32 v198, v118, v118
	v_fmac_f32_e32 v124, v196, v196
	v_fmac_f32_e32 v125, v194, v194
	v_add_f32_e32 v114, v114, v115
	v_add_f32_e32 v115, v193, v198
	v_add_f32_e32 v124, v124, v125
	v_add_f32_e32 v115, v115, v124
	v_add_f32_e32 v124, v114, v115
	v_mov_b32_e32 v125, v124
	s_nop 1
	v_permlane16_swap_b32_e32 v124, v125
	v_cvt_pk_bf16_f32 v114, v120, v121
	v_cvt_pk_bf16_f32 v115, v122, v123
	global_store_dwordx4 v[204:205], v[112:115], off
	s_waitcnt lgkmcnt(0)
	s_nop 0
	v_add_f32_e32 v112, v124, v125
	v_mov_b32_e32 v113, v112
	s_nop 1
	v_permlane32_swap_b32_e32 v112, v113
	v_cvt_pk_bf16_f32 v114, v116, v117
	v_cvt_pk_bf16_f32 v115, v118, v119
	v_cvt_pk_bf16_f32 v116, v196, v197
	v_cvt_pk_bf16_f32 v117, v194, v195
	global_store_dwordx4 v[204:205], v[114:117], off offset:64
	s_and_saveexec_b64 s[18:19], s[4:5]
	s_cbranch_execz .LBB0_1131
	s_add_u32 s26, s48, s25
	s_addc_u32 s27, s49, s24
	s_waitcnt lgkmcnt(0)
	v_add_f32_e32 v114, v112, v113
	v_lshl_add_u64 v[112:113], v[170:171], 2, s[26:27]
	global_store_dword v[112:113], v114, off
.LBB0_1131:
	s_or_b64 exec, exec, s[18:19]
	v_or_b32_e32 v112, 16, v178
	s_waitcnt lgkmcnt(0)
	v_ashrrev_i32_e32 v113, 31, v112
	v_lshlrev_b64 v[112:113], 11, v[112:113]
	v_lshl_add_u64 v[112:113], s[8:9], 0, v[112:113]
	v_lshl_add_u64 v[120:121], v[112:113], 0, v[174:175]
	global_load_dwordx4 v[116:119], v[120:121], off
	global_load_dwordx4 v[112:115], v[120:121], off offset:64
	v_lshlrev_b32_e32 v124, 16, v157
	v_and_b32_e32 v125, 0xffff0000, v157
	v_lshlrev_b32_e32 v122, 16, v156
	v_and_b32_e32 v123, 0xffff0000, v156
	v_pk_add_f32 v[110:111], v[110:111], v[124:125]
	v_lshlrev_b32_e32 v124, 16, v159
	v_and_b32_e32 v125, 0xffff0000, v159
	v_pk_add_f32 v[108:109], v[108:109], v[122:123]
	v_lshlrev_b32_e32 v122, 16, v158
	v_and_b32_e32 v123, 0xffff0000, v158
	v_pk_add_f32 v[106:107], v[106:107], v[124:125]
	v_lshlrev_b32_e32 v124, 16, v153
	v_and_b32_e32 v125, 0xffff0000, v153
	v_pk_add_f32 v[104:105], v[104:105], v[122:123]
	v_lshlrev_b32_e32 v122, 16, v152
	v_and_b32_e32 v123, 0xffff0000, v152
	v_pk_add_f32 v[102:103], v[102:103], v[124:125]
	v_lshlrev_b32_e32 v124, 16, v155
	v_and_b32_e32 v125, 0xffff0000, v155
	v_pk_add_f32 v[100:101], v[100:101], v[122:123]
	v_lshlrev_b32_e32 v122, 16, v154
	v_and_b32_e32 v123, 0xffff0000, v154
	v_pk_add_f32 v[124:125], v[98:99], v[124:125]
	v_mul_f32_e32 v98, v109, v109
	v_mul_f32_e32 v99, v111, v111
	v_pk_add_f32 v[122:123], v[96:97], v[122:123]
	v_lshl_add_u64 v[96:97], s[8:9], 0, v[182:183]
	v_fmac_f32_e32 v98, v108, v108
	v_fmac_f32_e32 v99, v110, v110
	v_lshl_add_u64 v[126:127], v[96:97], 0, v[174:175]
	v_cvt_pk_bf16_f32 v96, v108, v109
	v_add_f32_e32 v98, v98, v99
	v_mul_f32_e32 v99, v105, v105
	v_mul_f32_e32 v108, v107, v107
	v_fmac_f32_e32 v99, v104, v104
	v_fmac_f32_e32 v108, v106, v106
	v_add_f32_e32 v99, v99, v108
	v_add_f32_e32 v98, v98, v99
	v_mul_f32_e32 v99, v101, v101
	v_mul_f32_e32 v108, v103, v103
	v_fmac_f32_e32 v99, v100, v100
	v_fmac_f32_e32 v108, v102, v102
	v_add_f32_e32 v99, v99, v108
	v_mul_f32_e32 v108, v123, v123
	v_mul_f32_e32 v109, v125, v125
	v_fmac_f32_e32 v108, v122, v122
	v_fmac_f32_e32 v109, v124, v124
	v_add_f32_e32 v108, v108, v109
	v_add_f32_e32 v99, v99, v108
	v_add_f32_e32 v108, v98, v99
	v_mov_b32_e32 v109, v108
	s_nop 1
	v_permlane16_swap_b32_e32 v108, v109
	v_cvt_pk_bf16_f32 v97, v110, v111
	v_cvt_pk_bf16_f32 v98, v104, v105
	v_cvt_pk_bf16_f32 v99, v106, v107
	global_store_dwordx4 v[126:127], v[96:99], off
	s_waitcnt lgkmcnt(0)
	s_nop 0
	v_add_f32_e32 v96, v108, v109
	v_mov_b32_e32 v97, v96
	s_nop 1
	v_permlane32_swap_b32_e32 v96, v97
	v_cvt_pk_bf16_f32 v98, v100, v101
	v_cvt_pk_bf16_f32 v99, v102, v103
	v_cvt_pk_bf16_f32 v100, v122, v123
	v_cvt_pk_bf16_f32 v101, v124, v125
	global_store_dwordx4 v[126:127], v[98:101], off offset:64
	s_and_saveexec_b64 s[18:19], s[4:5]
	s_cbranch_execz .LBB0_1133
	s_add_u32 s26, s48, s25
	s_addc_u32 s27, s49, s24
	s_waitcnt lgkmcnt(0)
	v_add_f32_e32 v98, v96, v97
	v_lshl_add_u64 v[96:97], v[170:171], 2, s[26:27]
	global_store_dword v[96:97], v98, off offset:64
.LBB0_1133:
	s_or_b64 exec, exec, s[18:19]
	v_or_b32_e32 v96, 32, v178
	s_waitcnt lgkmcnt(0)
	v_ashrrev_i32_e32 v97, 31, v96
	v_lshlrev_b64 v[96:97], 11, v[96:97]
	v_lshl_add_u64 v[96:97], s[8:9], 0, v[96:97]
	v_lshl_add_u64 v[104:105], v[96:97], 0, v[174:175]
	global_load_dwordx4 v[100:103], v[104:105], off
	global_load_dwordx4 v[96:99], v[104:105], off offset:64
	v_lshlrev_b32_e32 v108, 16, v149
	v_and_b32_e32 v109, 0xffff0000, v149
	v_lshlrev_b32_e32 v106, 16, v148
	v_and_b32_e32 v107, 0xffff0000, v148
	v_pk_add_f32 v[94:95], v[94:95], v[108:109]
	v_lshlrev_b32_e32 v108, 16, v151
	v_and_b32_e32 v109, 0xffff0000, v151
	v_pk_add_f32 v[92:93], v[92:93], v[106:107]
	v_lshlrev_b32_e32 v106, 16, v150
	v_and_b32_e32 v107, 0xffff0000, v150
	v_pk_add_f32 v[90:91], v[90:91], v[108:109]
	v_lshlrev_b32_e32 v108, 16, v145
	v_and_b32_e32 v109, 0xffff0000, v145
	v_pk_add_f32 v[88:89], v[88:89], v[106:107]
	v_lshlrev_b32_e32 v106, 16, v144
	v_and_b32_e32 v107, 0xffff0000, v144
	v_pk_add_f32 v[86:87], v[86:87], v[108:109]
	v_lshlrev_b32_e32 v108, 16, v147
	v_and_b32_e32 v109, 0xffff0000, v147
	v_pk_add_f32 v[84:85], v[84:85], v[106:107]
	v_lshlrev_b32_e32 v106, 16, v146
	v_and_b32_e32 v107, 0xffff0000, v146
	v_pk_add_f32 v[108:109], v[82:83], v[108:109]
	v_mul_f32_e32 v82, v93, v93
	v_mul_f32_e32 v83, v95, v95
	v_pk_add_f32 v[106:107], v[80:81], v[106:107]
	v_lshl_add_u64 v[80:81], s[8:9], 0, v[180:181]
	v_fmac_f32_e32 v82, v92, v92
	v_fmac_f32_e32 v83, v94, v94
	v_lshl_add_u64 v[110:111], v[80:81], 0, v[174:175]
	v_cvt_pk_bf16_f32 v80, v92, v93
	v_add_f32_e32 v82, v82, v83
	v_mul_f32_e32 v83, v89, v89
	v_mul_f32_e32 v92, v91, v91
	v_fmac_f32_e32 v83, v88, v88
	v_fmac_f32_e32 v92, v90, v90
	v_add_f32_e32 v83, v83, v92
	v_add_f32_e32 v82, v82, v83
	v_mul_f32_e32 v83, v85, v85
	v_mul_f32_e32 v92, v87, v87
	v_fmac_f32_e32 v83, v84, v84
	v_fmac_f32_e32 v92, v86, v86
	v_add_f32_e32 v83, v83, v92
	v_mul_f32_e32 v92, v107, v107
	v_mul_f32_e32 v93, v109, v109
	v_fmac_f32_e32 v92, v106, v106
	v_fmac_f32_e32 v93, v108, v108
	v_add_f32_e32 v92, v92, v93
	v_add_f32_e32 v83, v83, v92
	v_add_f32_e32 v92, v82, v83
	v_mov_b32_e32 v93, v92
	s_nop 1
	v_permlane16_swap_b32_e32 v92, v93
	v_cvt_pk_bf16_f32 v81, v94, v95
	v_cvt_pk_bf16_f32 v82, v88, v89
	v_cvt_pk_bf16_f32 v83, v90, v91
	global_store_dwordx4 v[110:111], v[80:83], off
	s_waitcnt lgkmcnt(0)
	s_nop 0
	v_add_f32_e32 v80, v92, v93
	v_mov_b32_e32 v81, v80
	s_nop 1
	v_permlane32_swap_b32_e32 v80, v81
	v_cvt_pk_bf16_f32 v82, v84, v85
	v_cvt_pk_bf16_f32 v83, v86, v87
	v_cvt_pk_bf16_f32 v84, v106, v107
	v_cvt_pk_bf16_f32 v85, v108, v109
	global_store_dwordx4 v[110:111], v[82:85], off offset:64
	s_and_saveexec_b64 s[18:19], s[4:5]
	s_cbranch_execz .LBB0_1135
	s_add_u32 s26, s48, s25
	s_addc_u32 s27, s49, s24
	s_waitcnt lgkmcnt(0)
	v_add_f32_e32 v82, v80, v81
	v_lshl_add_u64 v[80:81], v[170:171], 2, s[26:27]
	global_store_dword v[80:81], v82, off offset:128
.LBB0_1135:
	s_or_b64 exec, exec, s[18:19]
	v_or_b32_e32 v80, 48, v178
	s_waitcnt lgkmcnt(0)
	v_ashrrev_i32_e32 v81, 31, v80
	v_lshlrev_b64 v[80:81], 11, v[80:81]
	v_lshl_add_u64 v[80:81], s[8:9], 0, v[80:81]
	v_lshl_add_u64 v[88:89], v[80:81], 0, v[174:175]
	global_load_dwordx4 v[84:87], v[88:89], off
	global_load_dwordx4 v[80:83], v[88:89], off offset:64
	v_lshlrev_b32_e32 v92, 16, v141
	v_and_b32_e32 v93, 0xffff0000, v141
	v_lshlrev_b32_e32 v90, 16, v140
	v_and_b32_e32 v91, 0xffff0000, v140
	v_pk_add_f32 v[78:79], v[78:79], v[92:93]
	v_lshlrev_b32_e32 v92, 16, v143
	v_and_b32_e32 v93, 0xffff0000, v143
	v_pk_add_f32 v[76:77], v[76:77], v[90:91]
	v_lshlrev_b32_e32 v90, 16, v142
	v_and_b32_e32 v91, 0xffff0000, v142
	v_pk_add_f32 v[74:75], v[74:75], v[92:93]
	s_waitcnt vmcnt(16)
	v_lshlrev_b32_e32 v92, 16, v137
	v_and_b32_e32 v93, 0xffff0000, v137
	v_pk_add_f32 v[72:73], v[72:73], v[90:91]
	v_lshlrev_b32_e32 v90, 16, v136
	v_and_b32_e32 v91, 0xffff0000, v136
	v_pk_add_f32 v[70:71], v[70:71], v[92:93]
	v_lshlrev_b32_e32 v92, 16, v139
	v_and_b32_e32 v93, 0xffff0000, v139
	v_pk_add_f32 v[68:69], v[68:69], v[90:91]
	v_lshlrev_b32_e32 v90, 16, v138
	v_and_b32_e32 v91, 0xffff0000, v138
	v_pk_add_f32 v[92:93], v[66:67], v[92:93]
	v_mul_f32_e32 v66, v77, v77
	v_mul_f32_e32 v67, v79, v79
	v_pk_add_f32 v[90:91], v[64:65], v[90:91]
	v_lshl_add_u64 v[64:65], s[8:9], 0, v[176:177]
	v_fmac_f32_e32 v66, v76, v76
	v_fmac_f32_e32 v67, v78, v78
	v_lshl_add_u64 v[94:95], v[64:65], 0, v[174:175]
	v_cvt_pk_bf16_f32 v64, v76, v77
	v_add_f32_e32 v66, v66, v67
	v_mul_f32_e32 v67, v73, v73
	v_mul_f32_e32 v76, v75, v75
	v_fmac_f32_e32 v67, v72, v72
	v_fmac_f32_e32 v76, v74, v74
	v_add_f32_e32 v67, v67, v76
	v_add_f32_e32 v66, v66, v67
	v_mul_f32_e32 v67, v69, v69
	v_mul_f32_e32 v76, v71, v71
	v_fmac_f32_e32 v67, v68, v68
	v_fmac_f32_e32 v76, v70, v70
	v_add_f32_e32 v67, v67, v76
	v_mul_f32_e32 v76, v91, v91
	v_mul_f32_e32 v77, v93, v93
	v_fmac_f32_e32 v76, v90, v90
	v_fmac_f32_e32 v77, v92, v92
	v_add_f32_e32 v76, v76, v77
	v_add_f32_e32 v67, v67, v76
	v_add_f32_e32 v76, v66, v67
	ds_bpermute_b32 v77, v192, v76
	v_cvt_pk_bf16_f32 v65, v78, v79
	v_cvt_pk_bf16_f32 v66, v72, v73
	v_cvt_pk_bf16_f32 v67, v74, v75
	global_store_dwordx4 v[94:95], v[64:67], off
	s_waitcnt lgkmcnt(0)
	s_nop 0
	v_add_f32_e32 v64, v76, v77
	v_mov_b32_e32 v65, v64
	s_nop 1
	v_permlane32_swap_b32_e32 v64, v65
	v_cvt_pk_bf16_f32 v66, v68, v69
	v_cvt_pk_bf16_f32 v67, v70, v71
	v_cvt_pk_bf16_f32 v68, v90, v91
	v_cvt_pk_bf16_f32 v69, v92, v93
	global_store_dwordx4 v[94:95], v[66:69], off offset:64
	s_and_saveexec_b64 s[18:19], s[4:5]
	s_cbranch_execz .LBB0_1137
	s_add_u32 s26, s48, s25
	s_addc_u32 s27, s49, s24
	s_waitcnt lgkmcnt(0)
	v_add_f32_e32 v66, v64, v65
	v_lshl_add_u64 v[64:65], v[170:171], 2, s[26:27]
	global_store_dword v[64:65], v66, off offset:192
.LBB0_1137:
	s_or_b64 exec, exec, s[18:19]
	s_waitcnt vmcnt(17)
	v_lshlrev_b32_e32 v66, 16, v133
	v_and_b32_e32 v67, 0xffff0000, v133
	v_pk_add_f32 v[62:63], v[62:63], v[66:67]
	v_lshlrev_b32_e32 v66, 16, v135
	v_and_b32_e32 v67, 0xffff0000, v135
	v_lshlrev_b32_e32 v64, 16, v132
	s_waitcnt lgkmcnt(0)
	v_and_b32_e32 v65, 0xffff0000, v132
	v_pk_add_f32 v[58:59], v[58:59], v[66:67]
	v_lshlrev_b32_e32 v66, 16, v129
	v_and_b32_e32 v67, 0xffff0000, v129
	v_pk_add_f32 v[60:61], v[60:61], v[64:65]
	v_lshlrev_b32_e32 v64, 16, v134
	v_and_b32_e32 v65, 0xffff0000, v134
	v_pk_add_f32 v[54:55], v[54:55], v[66:67]
	v_lshlrev_b32_e32 v66, 16, v131
	v_and_b32_e32 v67, 0xffff0000, v131
	v_pk_add_f32 v[56:57], v[56:57], v[64:65]
	v_lshlrev_b32_e32 v64, 16, v128
	v_and_b32_e32 v65, 0xffff0000, v128
	v_pk_add_f32 v[66:67], v[50:51], v[66:67]
	v_mul_f32_e32 v50, v61, v61
	v_mul_f32_e32 v51, v63, v63
	v_pk_add_f32 v[52:53], v[52:53], v[64:65]
	v_lshlrev_b32_e32 v64, 16, v130
	v_and_b32_e32 v65, 0xffff0000, v130
	v_fmac_f32_e32 v50, v60, v60
	v_fmac_f32_e32 v51, v62, v62
	v_pk_add_f32 v[64:65], v[48:49], v[64:65]
	v_cvt_pk_bf16_f32 v48, v60, v61
	v_add_f32_e32 v50, v50, v51
	v_mul_f32_e32 v51, v57, v57
	v_mul_f32_e32 v60, v59, v59
	v_fmac_f32_e32 v51, v56, v56
	v_fmac_f32_e32 v60, v58, v58
	v_add_f32_e32 v51, v51, v60
	v_add_f32_e32 v50, v50, v51
	v_mul_f32_e32 v51, v53, v53
	v_mul_f32_e32 v60, v55, v55
	v_fmac_f32_e32 v51, v52, v52
	v_fmac_f32_e32 v60, v54, v54
	v_add_f32_e32 v51, v51, v60
	v_mul_f32_e32 v60, v65, v65
	v_mul_f32_e32 v61, v67, v67
	v_fmac_f32_e32 v60, v64, v64
	v_fmac_f32_e32 v61, v66, v66
	v_add_f32_e32 v60, v60, v61
	v_add_f32_e32 v51, v51, v60
	v_add_f32_e32 v60, v50, v51
	ds_bpermute_b32 v61, v192, v60
	v_cvt_pk_bf16_f32 v49, v62, v63
	v_cvt_pk_bf16_f32 v50, v56, v57
	v_cvt_pk_bf16_f32 v51, v58, v59
	global_store_dwordx4 v[172:173], v[48:51], off
	s_waitcnt lgkmcnt(0)
	s_nop 0
	v_add_f32_e32 v48, v60, v61
	v_mov_b32_e32 v49, v48
	s_nop 1
	v_permlane32_swap_b32_e32 v48, v49
	v_cvt_pk_bf16_f32 v50, v52, v53
	v_cvt_pk_bf16_f32 v51, v54, v55
	v_cvt_pk_bf16_f32 v52, v64, v65
	v_cvt_pk_bf16_f32 v53, v66, v67
	global_store_dwordx4 v[172:173], v[50:53], off offset:64
	s_and_saveexec_b64 s[18:19], s[4:5]
	s_cbranch_execz .LBB0_1139
	s_add_u32 s26, s48, s25
	s_addc_u32 s27, s49, s24
	s_waitcnt lgkmcnt(0)
	v_add_f32_e32 v50, v48, v49
	v_lshl_add_u64 v[48:49], v[170:171], 2, s[26:27]
	global_store_dword v[48:49], v50, off offset:512
.LBB0_1139:
	s_or_b64 exec, exec, s[18:19]
	s_waitcnt vmcnt(13)
	v_lshlrev_b32_e32 v50, 16, v117
	v_and_b32_e32 v51, 0xffff0000, v117
	v_pk_add_f32 v[46:47], v[46:47], v[50:51]
	v_lshlrev_b32_e32 v50, 16, v119
	v_and_b32_e32 v51, 0xffff0000, v119
	v_lshlrev_b32_e32 v48, 16, v116
	s_waitcnt lgkmcnt(0)
	v_and_b32_e32 v49, 0xffff0000, v116
	v_pk_add_f32 v[42:43], v[42:43], v[50:51]
	s_waitcnt vmcnt(12)
	v_lshlrev_b32_e32 v50, 16, v113
	v_and_b32_e32 v51, 0xffff0000, v113
	v_pk_add_f32 v[44:45], v[44:45], v[48:49]
	v_lshlrev_b32_e32 v48, 16, v118
	v_and_b32_e32 v49, 0xffff0000, v118
	v_pk_add_f32 v[38:39], v[38:39], v[50:51]
	v_lshlrev_b32_e32 v50, 16, v115
	v_and_b32_e32 v51, 0xffff0000, v115
	v_pk_add_f32 v[40:41], v[40:41], v[48:49]
	v_lshlrev_b32_e32 v48, 16, v112
	v_and_b32_e32 v49, 0xffff0000, v112
	v_pk_add_f32 v[50:51], v[34:35], v[50:51]
	v_mul_f32_e32 v34, v45, v45
	v_mul_f32_e32 v35, v47, v47
	v_pk_add_f32 v[36:37], v[36:37], v[48:49]
	v_lshlrev_b32_e32 v48, 16, v114
	v_and_b32_e32 v49, 0xffff0000, v114
	v_fmac_f32_e32 v34, v44, v44
	v_fmac_f32_e32 v35, v46, v46
	v_pk_add_f32 v[48:49], v[32:33], v[48:49]
	v_cvt_pk_bf16_f32 v32, v44, v45
	v_add_f32_e32 v34, v34, v35
	v_mul_f32_e32 v35, v41, v41
	v_mul_f32_e32 v44, v43, v43
	v_fmac_f32_e32 v35, v40, v40
	v_fmac_f32_e32 v44, v42, v42
	v_add_f32_e32 v35, v35, v44
	v_add_f32_e32 v34, v34, v35
	v_mul_f32_e32 v35, v37, v37
	v_mul_f32_e32 v44, v39, v39
	v_fmac_f32_e32 v35, v36, v36
	v_fmac_f32_e32 v44, v38, v38
	v_add_f32_e32 v35, v35, v44
	v_mul_f32_e32 v44, v49, v49
	v_mul_f32_e32 v45, v51, v51
	v_fmac_f32_e32 v44, v48, v48
	v_fmac_f32_e32 v45, v50, v50
	v_add_f32_e32 v44, v44, v45
	v_add_f32_e32 v35, v35, v44
	v_add_f32_e32 v44, v34, v35
	ds_bpermute_b32 v45, v192, v44
	v_cvt_pk_bf16_f32 v33, v46, v47
	v_cvt_pk_bf16_f32 v34, v40, v41
	v_cvt_pk_bf16_f32 v35, v42, v43
	global_store_dwordx4 v[120:121], v[32:35], off
	s_waitcnt lgkmcnt(0)
	s_nop 0
	v_add_f32_e32 v32, v44, v45
	v_mov_b32_e32 v33, v32
	s_nop 1
	v_permlane32_swap_b32_e32 v32, v33
	v_cvt_pk_bf16_f32 v34, v36, v37
	v_cvt_pk_bf16_f32 v35, v38, v39
	v_cvt_pk_bf16_f32 v36, v48, v49
	v_cvt_pk_bf16_f32 v37, v50, v51
	global_store_dwordx4 v[120:121], v[34:37], off offset:64
	s_and_saveexec_b64 s[18:19], s[4:5]
	s_cbranch_execz .LBB0_1141
	s_add_u32 s26, s48, s25
	s_addc_u32 s27, s49, s24
	s_waitcnt lgkmcnt(0)
	v_add_f32_e32 v34, v32, v33
	v_lshl_add_u64 v[32:33], v[170:171], 2, s[26:27]
	global_store_dword v[32:33], v34, off offset:576
.LBB0_1141:
	s_or_b64 exec, exec, s[18:19]
	s_waitcnt vmcnt(11)
	v_lshlrev_b32_e32 v34, 16, v101
	v_and_b32_e32 v35, 0xffff0000, v101
	v_pk_add_f32 v[30:31], v[30:31], v[34:35]
	v_lshlrev_b32_e32 v34, 16, v103
	v_and_b32_e32 v35, 0xffff0000, v103
	v_lshlrev_b32_e32 v32, 16, v100
	s_waitcnt lgkmcnt(0)
	v_and_b32_e32 v33, 0xffff0000, v100
	v_pk_add_f32 v[26:27], v[26:27], v[34:35]
	s_waitcnt vmcnt(10)
	v_lshlrev_b32_e32 v34, 16, v97
	v_and_b32_e32 v35, 0xffff0000, v97
	v_pk_add_f32 v[28:29], v[28:29], v[32:33]
	v_lshlrev_b32_e32 v32, 16, v102
	v_and_b32_e32 v33, 0xffff0000, v102
	v_pk_add_f32 v[22:23], v[22:23], v[34:35]
	v_lshlrev_b32_e32 v34, 16, v99
	v_and_b32_e32 v35, 0xffff0000, v99
	v_pk_add_f32 v[24:25], v[24:25], v[32:33]
	v_lshlrev_b32_e32 v32, 16, v96
	v_and_b32_e32 v33, 0xffff0000, v96
	v_pk_add_f32 v[34:35], v[18:19], v[34:35]
	v_mul_f32_e32 v18, v29, v29
	v_mul_f32_e32 v19, v31, v31
	v_pk_add_f32 v[20:21], v[20:21], v[32:33]
	v_lshlrev_b32_e32 v32, 16, v98
	v_and_b32_e32 v33, 0xffff0000, v98
	v_fmac_f32_e32 v18, v28, v28
	v_fmac_f32_e32 v19, v30, v30
	v_pk_add_f32 v[32:33], v[16:17], v[32:33]
	v_cvt_pk_bf16_f32 v16, v28, v29
	v_add_f32_e32 v18, v18, v19
	v_mul_f32_e32 v19, v25, v25
	v_mul_f32_e32 v28, v27, v27
	v_fmac_f32_e32 v19, v24, v24
	v_fmac_f32_e32 v28, v26, v26
	v_add_f32_e32 v19, v19, v28
	v_add_f32_e32 v18, v18, v19
	v_mul_f32_e32 v19, v21, v21
	v_mul_f32_e32 v28, v23, v23
	v_fmac_f32_e32 v19, v20, v20
	v_fmac_f32_e32 v28, v22, v22
	v_add_f32_e32 v19, v19, v28
	v_mul_f32_e32 v28, v33, v33
	v_mul_f32_e32 v29, v35, v35
	v_fmac_f32_e32 v28, v32, v32
	v_fmac_f32_e32 v29, v34, v34
	v_add_f32_e32 v28, v28, v29
	v_add_f32_e32 v19, v19, v28
	v_add_f32_e32 v28, v18, v19
	ds_bpermute_b32 v29, v192, v28
	v_cvt_pk_bf16_f32 v17, v30, v31
	v_cvt_pk_bf16_f32 v18, v24, v25
	v_cvt_pk_bf16_f32 v19, v26, v27
	global_store_dwordx4 v[104:105], v[16:19], off
	s_waitcnt lgkmcnt(0)
	s_nop 0
	v_add_f32_e32 v16, v28, v29
	v_mov_b32_e32 v17, v16
	s_nop 1
	v_permlane32_swap_b32_e32 v16, v17
	v_cvt_pk_bf16_f32 v18, v20, v21
	v_cvt_pk_bf16_f32 v19, v22, v23
	v_cvt_pk_bf16_f32 v20, v32, v33
	v_cvt_pk_bf16_f32 v21, v34, v35
	global_store_dwordx4 v[104:105], v[18:21], off offset:64
	s_and_saveexec_b64 s[18:19], s[4:5]
	s_cbranch_execz .LBB0_1143
	s_add_u32 s26, s48, s25
	s_addc_u32 s27, s49, s24
	s_waitcnt lgkmcnt(0)
	v_add_f32_e32 v18, v16, v17
	v_lshl_add_u64 v[16:17], v[170:171], 2, s[26:27]
	global_store_dword v[16:17], v18, off offset:640
.LBB0_1143:
	s_or_b64 exec, exec, s[18:19]
	s_waitcnt vmcnt(9)
	v_lshlrev_b32_e32 v18, 16, v85
	v_and_b32_e32 v19, 0xffff0000, v85
	v_pk_add_f32 v[14:15], v[14:15], v[18:19]
	v_lshlrev_b32_e32 v18, 16, v87
	v_and_b32_e32 v19, 0xffff0000, v87
	v_lshlrev_b32_e32 v16, 16, v84
	s_waitcnt lgkmcnt(0)
	v_and_b32_e32 v17, 0xffff0000, v84
	v_pk_add_f32 v[10:11], v[10:11], v[18:19]
	s_waitcnt vmcnt(8)
	v_lshlrev_b32_e32 v18, 16, v81
	v_and_b32_e32 v19, 0xffff0000, v81
	v_pk_add_f32 v[12:13], v[12:13], v[16:17]
	v_lshlrev_b32_e32 v16, 16, v86
	v_and_b32_e32 v17, 0xffff0000, v86
	v_pk_add_f32 v[6:7], v[6:7], v[18:19]
	v_lshlrev_b32_e32 v18, 16, v83
	v_and_b32_e32 v19, 0xffff0000, v83
	v_pk_add_f32 v[8:9], v[8:9], v[16:17]
	v_lshlrev_b32_e32 v16, 16, v80
	v_and_b32_e32 v17, 0xffff0000, v80
	v_pk_add_f32 v[18:19], v[2:3], v[18:19]
	v_mul_f32_e32 v2, v13, v13
	v_mul_f32_e32 v3, v15, v15
	v_pk_add_f32 v[4:5], v[4:5], v[16:17]
	v_lshlrev_b32_e32 v16, 16, v82
	v_and_b32_e32 v17, 0xffff0000, v82
	v_fmac_f32_e32 v2, v12, v12
	v_fmac_f32_e32 v3, v14, v14
	v_pk_add_f32 v[16:17], v[0:1], v[16:17]
	v_cvt_pk_bf16_f32 v0, v12, v13
	v_add_f32_e32 v2, v2, v3
	v_mul_f32_e32 v3, v9, v9
	v_mul_f32_e32 v12, v11, v11
	v_fmac_f32_e32 v3, v8, v8
	v_fmac_f32_e32 v12, v10, v10
	v_add_f32_e32 v3, v3, v12
	v_add_f32_e32 v2, v2, v3
	v_mul_f32_e32 v3, v5, v5
	v_mul_f32_e32 v12, v7, v7
	v_fmac_f32_e32 v3, v4, v4
	v_fmac_f32_e32 v12, v6, v6
	v_add_f32_e32 v3, v3, v12
	v_mul_f32_e32 v12, v17, v17
	v_mul_f32_e32 v13, v19, v19
	v_fmac_f32_e32 v12, v16, v16
	v_fmac_f32_e32 v13, v18, v18
	v_add_f32_e32 v12, v12, v13
	v_add_f32_e32 v3, v3, v12
	v_add_f32_e32 v12, v2, v3
	v_mov_b32_e32 v13, v12
	s_nop 1
	v_permlane16_swap_b32_e32 v12, v13
	v_cvt_pk_bf16_f32 v1, v14, v15
	v_cvt_pk_bf16_f32 v2, v8, v9
	v_cvt_pk_bf16_f32 v3, v10, v11
	global_store_dwordx4 v[88:89], v[0:3], off
	s_waitcnt lgkmcnt(0)
	s_nop 0
	v_add_f32_e32 v0, v12, v13
	v_mov_b32_e32 v1, v0
	s_nop 1
	v_permlane32_swap_b32_e32 v0, v1
	v_cvt_pk_bf16_f32 v2, v4, v5
	v_cvt_pk_bf16_f32 v3, v6, v7
	v_cvt_pk_bf16_f32 v4, v16, v17
	v_cvt_pk_bf16_f32 v5, v18, v19
	global_store_dwordx4 v[88:89], v[2:5], off offset:64
	s_and_saveexec_b64 s[18:19], s[4:5]
	s_cbranch_execz .LBB0_1122
	s_add_u32 s26, s48, s25
	s_addc_u32 s27, s49, s24
	s_waitcnt lgkmcnt(0)
	v_add_f32_e32 v2, v0, v1
	v_lshl_add_u64 v[0:1], v[170:171], 2, s[26:27]
	global_store_dword v[0:1], v2, off offset:704
	s_branch .LBB0_1122
